# EpiAct: row scales kept in registers and reused while the workgroup stays on the same row panel
# speedup vs baseline: 1.0034x; 1.0024x over previous
; #define PG8_BAR __builtin_amdgcn_s_barrier()
;     __host__ __device__ bool next(int i, Unit& u) const {
;         const long L = (long)i * G + c; if (L >= nwg) return false;
;         int wgid = (int)L; { const int q = nwg / NXCD, r = nwg % NXCD, xcd = wgid % NXCD, off = wgid / NXCD; wgid = (xcd < r ? xcd * (q + 1) : r * (q + 1) + (xcd - r) * q) + off; }
; template <class Epi, class Sched, bool ALIGN_EPI = false, bool SP2 = false>
; __device__ __forceinline__ void gemm_phase(PG8_LAS unsigned char* lds, const Gemm g, const Sched& S, const Epi& E) {
;     int tid_ = threadIdx.x; asm volatile("" : "+v"(tid_));
;     const int tid = tid_, wid = __builtin_amdgcn_readfirstlane(tid >> 6), lane = tid & 63, wr = wid >> 2, wc = wid & 3, fr = lane & 15, fq = lane >> 4;
;     int K_ = g.K; asm volatile("" : "+s"(K_));
;     const int K = K_, nt = K / BK;
;     unsigned voffA[2], voffB[2];
; #pragma unroll
;     for (int i = 0; i < 2; ++i) { int R, C; stage_rc(tid * 16 + i * 8192, R, C); const int Rb = Epi::PERM ? ((R & ~31) + perm32(R & 31)) : R;
;         voffA[i] = (unsigned)(R * K + C) * 2u; voffB[i] = (unsigned)(Rb * K + C) * 2u; }
;     const size_t kstep = (size_t)(BK * 2);
;     const size_t hstep = (size_t)HALF * K * 2;
;     const size_t tstep = 2 * hstep;
;     const unsigned ldsw = (unsigned)wid * 1024u;
;     const int aoff = lds_byte(wr * 64 + fr, fq * 8), boff = lds_byte(wc * 32 + fr, fq * 8);
;     ...
;     Unit cur, nxt; int ui = 0;
;     if (!S.next(0, cur)) return;
;     f32x4 acc[2][2][4][2];
; #pragma unroll
;     for (int a = 0; a < 2; ++a)
; #pragma unroll
;         for (int b = 0; b < 2; ++b)
; #pragma unroll
;             for (int m = 0; m < 4; ++m)
; #pragma unroll
;                 for (int n = 0; n < 2; ++n) acc[a][b][m][n] = (f32x4){0.f, 0.f, 0.f, 0.f};
;     bf16x8 At[4][2], B0[2][2], B1[2][2];
;     const char* cA = (const char*)g.A + (size_t)cur.pm * tstep; const char* cB = (const char*)g.Bt + (size_t)cur.pn * tstep;
;     S.a_ready(cur);
;     if constexpr (SP2) {
;         PG8_STAGE(PG8_SB(0, 0), cB, voffB); PG8_STAGE(PG8_SB(0, 1), cB + hstep, voffB); PG8_STAGE(PG8_SA(0, 0), cA, voffA); PG8_STAGE(PG8_SA(0, 1), cA + hstep, voffA);
;         if (wr == 1) PG8_BAR;
;         PG8_WAIT_V(2); PG8_BAR;
;         PG8_STAGE(PG8_SB(1, 0), cB + kstep, voffB); PG8_STAGE(PG8_SA(1, 0), cA + kstep, voffA); PG8_STAGE(PG8_SB(1, 1), cB + hstep + kstep, voffB);
.LBB0_249:
	s_cmp_lt_i32 s28, 2
	s_cselect_b64 s[4:5], -1, 0
	s_add_u32 s52, s26, 0x2900000
	s_addc_u32 s53, s27, 0
	s_add_u32 s46, s26, 0x8680000
	s_addc_u32 s47, s27, 0
	s_cmpk_eq_i32 s30, 0x100
	s_cselect_b64 s[54:55], -1, 0
	s_cmpk_lg_i32 s30, 0x100
	s_cselect_b64 s[50:51], -1, 0
	s_and_b64 s[10:11], s[4:5], s[6:7]
	s_andn2_b64 vcc, exec, s[10:11]
	s_cbranch_vccnz .LBB0_291
	s_mov_b32 s86, -1
	v_lshlrev_b32_e32 v236, 4, v192
	v_mov_b32_e32 v237, 0
	v_lshl_add_u64 v[236:237], s[44:45], 0, v[236:237]
	v_mov_b32_e32 v12, v192
	s_movk_i32 s6, 0x400
	v_readfirstlane_b32 s9, v12
	s_cmpk_gt_i32 s2, 0x5d7
	s_cbranch_scc1 .LBB0_271
	v_lshlrev_b32_e32 v0, 4, v12
	v_add_u32_e32 v1, 0x2000, v0
	v_ashrrev_i32_e32 v2, 31, v1
	v_lshrrev_b32_e32 v2, 22, v2
	v_add_u32_e32 v2, v1, v2
	v_ashrrev_i32_e32 v2, 10, v2
	v_mul_i32_i24_e32 v3, 0x400, v2
	v_sub_u32_e32 v1, v1, v3
	v_lshrrev_b32_e32 v3, 4, v1
	v_bitop3_b32 v1, v3, v1, 32 bitop3:0x6c
	v_ashrrev_i32_e32 v3, 31, v1
	v_lshrrev_b32_e32 v3, 26, v3
	v_add_u32_e32 v3, v1, v3
	v_lshlrev_b32_e32 v5, 3, v2
	v_ashrrev_i32_e32 v4, 6, v3
	v_and_b32_e32 v5, -16, v5
	v_lshlrev_b32_e32 v2, 5, v2
	v_add_u32_e32 v5, v4, v5
	v_and_b32_e32 v13, 32, v2
	v_and_b32_e32 v2, 0xc0, v3
	v_and_b32_e32 v4, 3, v4
	s_mov_b32 s4, 0x7fffffe0
	v_lshrrev_b32_e32 v6, 2, v5
	v_lshlrev_b32_e32 v7, 1, v5
	v_sub_u32_e32 v1, v1, v2
	v_mov_b32_e32 v2, 1
	v_and_or_b32 v4, v5, s4, v4
	v_and_b32_e32 v6, 4, v6
	v_and_b32_e32 v7, 24, v7
	v_ashrrev_i16_sdwa v1, v2, sext(v1) dst_sel:DWORD dst_unused:UNUSED_PAD src0_sel:DWORD src1_sel:BYTE_0
	v_or3_b32 v4, v4, v6, v7
	v_bfe_i32 v14, v1, 0, 16
	v_mul_lo_u32 v4, v4, s6
	v_add_u32_e32 v1, v13, v14
	v_mul_lo_u32 v15, v5, s6
	v_add_lshl_u32 v130, v4, v1, 1
	v_add_lshl_u32 v132, v1, v15, 1
	v_bfe_i32 v1, v12, 27, 1
	v_lshrrev_b32_e32 v1, 22, v1
	v_add_u32_e32 v1, v0, v1
	v_and_b32_e32 v1, 0xfffffc00, v1
	v_sub_u32_e32 v0, v0, v1
	v_lshrrev_b32_e32 v1, 4, v0
	v_ashrrev_i32_e32 v4, 31, v12
	v_bitop3_b32 v0, v1, v0, 32 bitop3:0x6c
	v_lshrrev_b32_e32 v4, 26, v4
	v_ashrrev_i32_e32 v1, 31, v0
	v_add_u32_e32 v4, v12, v4
	v_lshrrev_b32_e32 v1, 26, v1
	v_ashrrev_i32_e32 v4, 6, v4
	v_add_u32_e32 v1, v0, v1
	v_lshlrev_b32_e32 v5, 3, v4
	v_ashrrev_i32_e32 v3, 6, v1
	v_and_b32_e32 v5, -16, v5
	v_add_u32_e32 v5, v3, v5
	v_and_b32_e32 v3, 3, v3
	s_ashr_i32 s39, s2, 31
	v_and_or_b32 v3, v5, s4, v3
	s_lshr_b32 s4, s39, 29
	s_add_i32 s4, s2, s4
	s_ashr_i32 s20, s9, 6
	s_ashr_i32 s7, s6, 31
	s_ashr_i32 s5, s4, 3
	s_and_b32 s4, s4, -8
	s_ashr_i32 s21, s9, 8
	s_lshl_b64 s[12:13], s[6:7], 8
	s_lshl_b64 s[14:15], s[6:7], 9
	s_lshl_b32 s3, s20, 10
	s_sub_i32 s4, s2, s4
	s_cmp_lt_i32 s4, 0
	s_movk_i32 s49, 0xbc
	s_cselect_b32 s8, s49, 0xbb
	s_mul_i32 s4, s4, s8
	s_add_i32 s4, s4, s5
	s_mul_hi_i32 s5, s4, 0x2e8ba2e9
	s_lshr_b32 s8, s5, 31
	s_ashr_i32 s5, s5, 5
	v_and_b32_e32 v1, 0xc0, v1
	s_add_i32 s5, s5, s8
	v_lshrrev_b32_e32 v6, 2, v5
	v_lshlrev_b32_e32 v7, 1, v5
	v_sub_u32_e32 v0, v0, v1
	s_lshl_b32 s16, s5, 3
	v_and_b32_e32 v6, 4, v6
	v_and_b32_e32 v7, 24, v7
	v_lshlrev_b32_e32 v4, 5, v4
	v_ashrrev_i16_sdwa v0, v2, sext(v0) dst_sel:DWORD dst_unused:UNUSED_PAD src0_sel:DWORD src1_sel:BYTE_0
	s_sub_i32 s8, 0x44, s16
	s_mulk_i32 s5, 0xb0
	v_or3_b32 v3, v3, v6, v7
	v_and_b32_e32 v16, 32, v4
	v_bfe_i32 v17, v0, 0, 16
	s_min_u32 s17, s8, 8
	s_sub_i32 s18, s4, s5
	v_mul_lo_u32 v3, v3, s6
	v_add_u32_e32 v0, v16, v17
	s_sext_i32_i16 s4, s18
	v_cvt_f32_ubyte0_e32 v2, s17
	v_add_lshl_u32 v134, v3, v0, 1
	v_cvt_f32_i32_e32 v1, s4
	v_rcp_iflag_f32_e32 v3, v2
	v_mul_lo_u32 v18, v5, s6
	v_add_lshl_u32 v136, v0, v18, 1
	s_ashr_i32 s4, s4, 30
	v_mul_f32_e32 v0, v1, v3
	v_trunc_f32_e32 v0, v0
	v_fma_f32 v1, -v0, v2, v1
	v_cvt_i32_f32_e32 v0, v0
	s_or_b32 s8, s4, 1
	v_cmp_ge_f32_e64 s[4:5], |v1|, v2
	s_and_b64 s[4:5], s[4:5], exec
	s_cselect_b32 s4, s8, 0
	v_readfirstlane_b32 s5, v0
	s_add_i32 s8, s5, s4
	s_mul_i32 s4, s8, s17
	s_sub_i32 s4, s18, s4
	s_sext_i32_i16 s4, s4
	s_add_i32 s4, s16, s4
	s_ashr_i32 s5, s4, 31
	s_mul_i32 s5, s14, s5
	s_mul_hi_u32 s16, s14, s4
	s_add_i32 s5, s16, s5
	s_lshr_b64 s[16:17], s[6:7], 23
	s_mul_i32 s17, s16, s4
	s_bfe_i64 s[18:19], s[8:9], 0x100000
	s_add_i32 s5, s5, s17
	s_mul_i32 s17, s14, s19
	s_mul_hi_u32 s19, s14, s18
	s_add_i32 s17, s19, s17
	s_mul_i32 s16, s16, s18
	s_add_i32 s17, s17, s16
	s_mul_i32 s16, s14, s18
	s_add_u32 s42, s26, s16
	s_addc_u32 s43, s27, s17
	s_add_i32 s56, s3, 0
	s_add_i32 m0, s56, 0x10000
	s_mul_i32 s22, s14, s4
	global_load_lds_dwordx4 v134, s[42:43]
	s_add_i32 m0, s56, 0x12000
	s_add_u32 s16, s42, s12
	global_load_lds_dwordx4 v130, s[42:43]
	s_addc_u32 s17, s43, s13
	s_add_i32 m0, s56, 0x14000
	v_mov_b32_e32 v135, 0
	global_load_lds_dwordx4 v134, s[16:17]
	s_add_i32 m0, s56, 0x16000
	s_add_u32 s40, s34, s22
	s_addc_u32 s41, s35, s5
	s_add_i32 s57, s56, 0x2000
	global_load_lds_dwordx4 v130, s[16:17]
	s_mov_b32 m0, s56
	s_add_u32 s18, s40, s12
	global_load_lds_dwordx4 v136, s[40:41]
	s_mov_b32 m0, s57
	s_addc_u32 s19, s41, s13
	s_add_i32 s58, s56, 0x4000
	global_load_lds_dwordx4 v132, s[40:41]
	s_mov_b32 m0, s58
	s_add_i32 s59, s56, 0x6000
	global_load_lds_dwordx4 v136, s[18:19]
	s_mov_b32 m0, s59
	v_mov_b32_e32 v131, v135
	global_load_lds_dwordx4 v132, s[18:19]
	v_mov_b32_e32 v137, v135
	v_mov_b32_e32 v133, v135
	s_cmp_eq_u32 s21, 1
	s_mov_b32 s60, 0
	v_lshl_add_u64 v[8:9], s[42:43], 0, v[134:135]
	v_lshl_add_u64 v[4:5], s[42:43], 0, v[130:131]
	v_lshl_add_u64 v[2:3], s[16:17], 0, v[134:135]
	v_lshl_add_u64 v[0:1], s[16:17], 0, v[130:131]
	v_lshl_add_u64 v[6:7], s[40:41], 0, v[136:137]
	s_cselect_b64 s[16:17], -1, 0
	s_cmp_lg_u32 s21, 1
	v_lshl_add_u64 v[10:11], s[40:41], 0, v[132:133]
	s_cbranch_scc1 .LBB0_253
	s_barrier

; __device__ __forceinline__ void row_rs8(const float* SS, int row0, int fq, float (&rsv)[2][4]) {
;     f32x4 q[2][4];
; #pragma unroll
;     for (int ai = 0; ai < 2; ++ai)
; #pragma unroll
;         for (int m = 0; m < 4; ++m) q[ai][m] = *(const f32x4*)(SS + (size_t)(row0 + ai * HALF + m * 16) * 16 + 4 * fq);
; #pragma unroll
;     for (int ai = 0; ai < 2; ++ai)
; #pragma unroll
;         for (int m = 0; m < 4; ++m) { float t = (q[ai][m][0] + q[ai][m][1]) + (q[ai][m][2] + q[ai][m][3]); t += __shfl_xor(t, 16); t += __shfl_xor(t, 32); rsv[ai][m] = __builtin_amdgcn_rsqf(t * (1.0f / 1024.0f) + 1e-6f); }
; }
;     __device__ __forceinline__ void operator()(const f32x4 (&acc)[2][2][4][2], const Unit& u, int wr, int wc, int fr, int fq) const {
;         const int row0 = u.pm * BM + wr * 64 + fr, col0 = u.pn * HALF + wc * 32 + 8 * fq;
;         float rsv[2][4]; row_rs8(SS, row0, fq, rsv);
; #pragma unroll
;         for (int ai = 0; ai < 2; ++ai)
; #pragma unroll
;             for (int m = 0; m < 4; ++m) {
;                 const int r = row0 + ai * HALF + m * 16; const float rs = rsv[ai][m], nrs = rs * -1.4426950408889634f, rs2 = rs * rs;
.LBB0_267:
	v_lshl_add_u32 v162, s4, 8, v129
	v_or_b32_e32 v160, 16, v162
	v_or_b32_e32 v158, 32, v162
	v_or_b32_e32 v156, 48, v162
	v_add_u32_e32 v154, 0x80, v162
	v_add_u32_e32 v152, 0x90, v162
	v_add_u32_e32 v150, 0xa0, v162
	v_add_u32_e32 v148, 0xb0, v162
	v_lshl_or_b32 v250, s5, 7, v167
	v_lshlrev_b32_e32 v250, 1, v250
	v_mov_b32_e32 v251, 0
	v_mov_b64_e32 v[220:221], s[52:53]
	s_and_b64 vcc, exec, s[6:7]
	s_mov_b64 s[6:7], -1
	s_cmp_eq_u32 s4, s86
	s_cbranch_scc1 .Lrs_reuse_p1
	s_mov_b32 s86, s4
	v_and_b32_e32 v252, 48, v192
	v_lshl_add_u32 v252, v129, 6, v252
	v_add_u32_e32 v252, 0x20000, v252
	ds_read_b128 v[174:177], v252
	ds_read_b128 v[178:181], v252 offset:1024
	ds_read_b128 v[182:185], v252 offset:2048
	ds_read_b128 v[186:189], v252 offset:3072
	ds_read_b128 v[194:197], v252 offset:8192
	ds_read_b128 v[198:201], v252 offset:9216
	ds_read_b128 v[202:205], v252 offset:10240
	ds_read_b128 v[206:209], v252 offset:11264
	v_xor_b32_e32 v210, 16, v171
	v_xor_b32_e32 v211, 32, v171
	v_lshlrev_b32_e32 v210, 2, v210
	v_lshlrev_b32_e32 v211, 2, v211
	s_waitcnt lgkmcnt(0)
	v_pk_add_f32 v[174:175], v[174:175], v[176:177]
	v_pk_add_f32 v[178:179], v[178:179], v[180:181]
	v_pk_add_f32 v[182:183], v[182:183], v[184:185]
	v_pk_add_f32 v[186:187], v[186:187], v[188:189]
	v_pk_add_f32 v[194:195], v[194:195], v[196:197]
	v_pk_add_f32 v[198:199], v[198:199], v[200:201]
	v_pk_add_f32 v[202:203], v[202:203], v[204:205]
	v_pk_add_f32 v[206:207], v[206:207], v[208:209]
	v_add_f32_e32 v242, v174, v175
	v_add_f32_e32 v243, v178, v179
	v_add_f32_e32 v244, v182, v183
	v_add_f32_e32 v245, v186, v187
	v_add_f32_e32 v246, v194, v195
	v_add_f32_e32 v247, v198, v199
	v_add_f32_e32 v248, v202, v203
	v_add_f32_e32 v249, v206, v207
	ds_bpermute_b32 v222, v210, v242
	ds_bpermute_b32 v223, v210, v243
	ds_bpermute_b32 v224, v210, v244
	ds_bpermute_b32 v225, v210, v245
	ds_bpermute_b32 v226, v210, v246
	ds_bpermute_b32 v227, v210, v247
	ds_bpermute_b32 v228, v210, v248
	ds_bpermute_b32 v229, v210, v249
	s_waitcnt lgkmcnt(7)
	v_add_f32_e32 v242, v242, v222
	s_waitcnt lgkmcnt(6)
	v_add_f32_e32 v243, v243, v223
	s_waitcnt lgkmcnt(5)
	v_add_f32_e32 v244, v244, v224
	s_waitcnt lgkmcnt(4)
	v_add_f32_e32 v245, v245, v225
	s_waitcnt lgkmcnt(3)
	v_add_f32_e32 v246, v246, v226
	s_waitcnt lgkmcnt(2)
	v_add_f32_e32 v247, v247, v227
	s_waitcnt lgkmcnt(1)
	v_add_f32_e32 v248, v248, v228
	s_waitcnt lgkmcnt(0)
	v_add_f32_e32 v249, v249, v229
	ds_bpermute_b32 v222, v211, v242
	ds_bpermute_b32 v223, v211, v243
	ds_bpermute_b32 v224, v211, v244
	ds_bpermute_b32 v225, v211, v245
	ds_bpermute_b32 v226, v211, v246
	ds_bpermute_b32 v227, v211, v247
	ds_bpermute_b32 v228, v211, v248
	ds_bpermute_b32 v229, v211, v249
	s_waitcnt lgkmcnt(7)
	v_add_f32_e32 v242, v242, v222
	s_waitcnt lgkmcnt(6)
	v_add_f32_e32 v243, v243, v223
	s_waitcnt lgkmcnt(5)
	v_add_f32_e32 v244, v244, v224
	s_waitcnt lgkmcnt(4)
	v_add_f32_e32 v245, v245, v225
	s_waitcnt lgkmcnt(3)
	v_add_f32_e32 v246, v246, v226
	s_waitcnt lgkmcnt(2)
	v_add_f32_e32 v247, v247, v227
	s_waitcnt lgkmcnt(1)
	v_add_f32_e32 v248, v248, v228
	s_waitcnt lgkmcnt(0)
	v_add_f32_e32 v249, v249, v229
	v_fmamk_f32 v242, v242, 0x3a800000, v172
	v_fmamk_f32 v243, v243, 0x3a800000, v172
	v_fmamk_f32 v244, v244, 0x3a800000, v172
	v_fmamk_f32 v245, v245, 0x3a800000, v172
	v_fmamk_f32 v246, v246, 0x3a800000, v172
	v_fmamk_f32 v247, v247, 0x3a800000, v172
	v_fmamk_f32 v248, v248, 0x3a800000, v172
	v_fmamk_f32 v249, v249, 0x3a800000, v172
	v_rsq_f32_e32 v242, v242
	v_rsq_f32_e32 v243, v243
	v_rsq_f32_e32 v244, v244
	v_rsq_f32_e32 v245, v245
	v_rsq_f32_e32 v246, v246
	v_rsq_f32_e32 v247, v247
	v_rsq_f32_e32 v248, v248
	v_rsq_f32_e32 v249, v249
.Lrs_reuse_p1:
	v_pk_mul_f32 v[124:125], v[124:125], v[120:121]
	v_pk_mul_f32 v[126:127], v[126:127], v[122:123]
	v_pk_mul_f32 v[112:113], v[112:113], v[116:117]
	v_pk_mul_f32 v[114:115], v[114:115], v[118:119]
	v_pk_mul_f32 v[104:105], v[104:105], v[108:109]
	v_pk_mul_f32 v[106:107], v[106:107], v[110:111]
	v_pk_mul_f32 v[96:97], v[96:97], v[100:101]
	v_pk_mul_f32 v[98:99], v[98:99], v[102:103]
	v_pk_mul_f32 v[88:89], v[88:89], v[92:93]
	v_pk_mul_f32 v[90:91], v[90:91], v[94:95]
	v_pk_mul_f32 v[80:81], v[80:81], v[84:85]
	v_pk_mul_f32 v[82:83], v[82:83], v[86:87]
	v_pk_mul_f32 v[72:73], v[72:73], v[76:77]
	v_pk_mul_f32 v[74:75], v[74:75], v[78:79]
	v_pk_mul_f32 v[64:65], v[64:65], v[68:69]
	v_pk_mul_f32 v[66:67], v[66:67], v[70:71]
	v_pk_mul_f32 v[56:57], v[56:57], v[60:61]
	v_pk_mul_f32 v[58:59], v[58:59], v[62:63]
	v_pk_mul_f32 v[48:49], v[48:49], v[52:53]
	v_pk_mul_f32 v[50:51], v[50:51], v[54:55]
	v_pk_mul_f32 v[40:41], v[40:41], v[44:45]
	v_pk_mul_f32 v[42:43], v[42:43], v[46:47]
	v_pk_mul_f32 v[32:33], v[32:33], v[36:37]
	v_pk_mul_f32 v[34:35], v[34:35], v[38:39]
	v_pk_mul_f32 v[24:25], v[24:25], v[28:29]
	v_pk_mul_f32 v[26:27], v[26:27], v[30:31]
	v_pk_mul_f32 v[16:17], v[16:17], v[20:21]
	v_pk_mul_f32 v[18:19], v[18:19], v[22:23]
	v_pk_mul_f32 v[8:9], v[8:9], v[12:13]
	v_pk_mul_f32 v[10:11], v[10:11], v[14:15]
	v_pk_mul_f32 v[0:1], v[0:1], v[4:5]
	v_pk_mul_f32 v[2:3], v[2:3], v[6:7]
	v_mul_f32_e32 v230, 0xbfb8aa3b, v242
	v_mul_f32_e32 v231, v242, v242
	v_mul_f32_e32 v232, 0xbfb8aa3b, v243
	v_mul_f32_e32 v233, v243, v243
	v_mul_f32_e32 v234, 0xbfb8aa3b, v244
	v_mul_f32_e32 v235, v244, v244
	v_mul_f32_e32 v184, 0xbfb8aa3b, v245
	v_mul_f32_e32 v185, v245, v245
	v_mul_f32_e32 v186, 0xbfb8aa3b, v246
	v_mul_f32_e32 v187, v246, v246
	v_mul_f32_e32 v188, 0xbfb8aa3b, v247
	v_mul_f32_e32 v189, v247, v247
	v_mul_f32_e32 v190, 0xbfb8aa3b, v248
	v_mul_f32_e32 v191, v248, v248
	v_mul_f32_e32 v204, 0xbfb8aa3b, v249
; __device__ __forceinline__ unsigned cvt_pk_bf16(float lo, float hi) { unsigned r; asm volatile("v_cvt_pk_bf16_f32 %0, %1, %2" : "=v"(r) : "v"(lo), "v"(hi)); return r; }
; __device__ __forceinline__ float fast_rcp(float x) { return __builtin_amdgcn_rcpf(x); }
; __device__ __forceinline__ unsigned cvt_pk_bf16(float lo, float hi) { const f32x2 v = {lo, hi}; const bf16x2_t b = __builtin_convertvector(v, bf16x2_t); return __builtin_bit_cast(unsigned, b); }
;     __device__ __forceinline__ void operator()(const f32x4 (&acc)[2][2][4][2], const Unit& u, int wr, int wc, int fr, int fq) const {
;     ...
;             for (int m = 0; m < 4; ++m) {
;                 const int r = row0 + ai * HALF + m * 16; const float rs = rsv[ai][m], nrs = rs * -1.4426950408889634f, rs2 = rs * rs;
;                 float o[8];
; #pragma unroll
;                 for (int n = 0; n < 2; ++n) {
;                     const f32x4 t = acc[ai][0][m][n] * nrs, p = (acc[ai][0][m][n] * acc[ai][1][m][n]) * rs2;
; #pragma unroll
;                     for (int j = 0; j < 4; ++j) o[4 * n + j] = p[j] * fast_rcp(1.0f + __builtin_amdgcn_exp2f(t[j]));
;                 }
;                 u32x4 w; w.x = cvt_pk_bf16(o[0], o[1]); w.y = cvt_pk_bf16(o[2], o[3]); w.z = cvt_pk_bf16(o[4], o[5]); w.w = cvt_pk_bf16(o[6], o[7]);
;                 *(u32x4*)(O + (size_t)r * ldo + col0) = w;
	v_mul_f32_e32 v205, v249, v249
	v_pk_mul_f32 v[120:121], v[120:121], v[230:231] op_sel_hi:[1,0]
	v_pk_mul_f32 v[122:123], v[122:123], v[230:231] op_sel_hi:[1,0]
	v_pk_mul_f32 v[116:117], v[116:117], v[230:231] op_sel_hi:[1,0]
	v_pk_mul_f32 v[118:119], v[118:119], v[230:231] op_sel_hi:[1,0]
	v_exp_f32_e32 v120, v120
	v_exp_f32_e32 v121, v121
	v_exp_f32_e32 v122, v122
	v_exp_f32_e32 v123, v123
	v_exp_f32_e32 v116, v116
	v_exp_f32_e32 v117, v117
	v_exp_f32_e32 v118, v118
	v_exp_f32_e32 v119, v119
	v_pk_mul_f32 v[124:125], v[124:125], v[230:231] op_sel:[0,1] op_sel_hi:[1,1]
	v_pk_mul_f32 v[126:127], v[126:127], v[230:231] op_sel:[0,1] op_sel_hi:[1,1]
	v_pk_mul_f32 v[112:113], v[112:113], v[230:231] op_sel:[0,1] op_sel_hi:[1,1]
	v_pk_mul_f32 v[114:115], v[114:115], v[230:231] op_sel:[0,1] op_sel_hi:[1,1]
	v_pk_add_f32 v[120:121], v[120:121], 1.0 op_sel_hi:[1,0]
	v_pk_add_f32 v[122:123], v[122:123], 1.0 op_sel_hi:[1,0]
	v_pk_add_f32 v[116:117], v[116:117], 1.0 op_sel_hi:[1,0]
	v_pk_add_f32 v[118:119], v[118:119], 1.0 op_sel_hi:[1,0]
	v_rcp_f32_e32 v120, v120
	v_rcp_f32_e32 v121, v121
	v_rcp_f32_e32 v122, v122
	v_rcp_f32_e32 v123, v123
	v_rcp_f32_e32 v116, v116
	v_rcp_f32_e32 v117, v117
	v_rcp_f32_e32 v118, v118
	v_rcp_f32_e32 v119, v119
	v_mad_i64_i32 v[208:209], s[4:5], v162, s68, v[220:221]
	v_lshl_add_u64 v[208:209], v[208:209], 0, v[250:251]
	v_pk_mul_f32 v[124:125], v[124:125], v[120:121]
	v_pk_mul_f32 v[126:127], v[126:127], v[122:123]
	v_pk_mul_f32 v[112:113], v[112:113], v[116:117]
	v_pk_mul_f32 v[114:115], v[114:115], v[118:119]
	v_cvt_pk_bf16_f32 v120, v124, v125
	v_cvt_pk_bf16_f32 v121, v126, v127
	v_cvt_pk_bf16_f32 v122, v112, v113
	v_cvt_pk_bf16_f32 v123, v114, v115
	global_store_dwordx4 v[208:209], v[120:123], off
	v_pk_mul_f32 v[108:109], v[108:109], v[232:233] op_sel_hi:[1,0]
	v_pk_mul_f32 v[110:111], v[110:111], v[232:233] op_sel_hi:[1,0]
	v_pk_mul_f32 v[100:101], v[100:101], v[232:233] op_sel_hi:[1,0]
	v_pk_mul_f32 v[102:103], v[102:103], v[232:233] op_sel_hi:[1,0]
	v_exp_f32_e32 v108, v108
	v_exp_f32_e32 v109, v109
	v_exp_f32_e32 v110, v110
	v_exp_f32_e32 v111, v111
	v_exp_f32_e32 v100, v100
	v_exp_f32_e32 v101, v101
	v_exp_f32_e32 v102, v102
	v_exp_f32_e32 v103, v103
	v_pk_mul_f32 v[104:105], v[104:105], v[232:233] op_sel:[0,1] op_sel_hi:[1,1]
	v_pk_mul_f32 v[106:107], v[106:107], v[232:233] op_sel:[0,1] op_sel_hi:[1,1]
	v_pk_mul_f32 v[96:97], v[96:97], v[232:233] op_sel:[0,1] op_sel_hi:[1,1]
	v_pk_mul_f32 v[98:99], v[98:99], v[232:233] op_sel:[0,1] op_sel_hi:[1,1]
	v_pk_add_f32 v[108:109], v[108:109], 1.0 op_sel_hi:[1,0]
	v_pk_add_f32 v[110:111], v[110:111], 1.0 op_sel_hi:[1,0]
	v_pk_add_f32 v[100:101], v[100:101], 1.0 op_sel_hi:[1,0]
	v_pk_add_f32 v[102:103], v[102:103], 1.0 op_sel_hi:[1,0]
	v_rcp_f32_e32 v108, v108
	v_rcp_f32_e32 v109, v109
	v_rcp_f32_e32 v110, v110
	v_rcp_f32_e32 v111, v111
	v_rcp_f32_e32 v100, v100
	v_rcp_f32_e32 v101, v101
	v_rcp_f32_e32 v102, v102
	v_rcp_f32_e32 v103, v103
	v_mad_i64_i32 v[208:209], s[4:5], v160, s68, v[220:221]
	v_lshl_add_u64 v[208:209], v[208:209], 0, v[250:251]
	v_pk_mul_f32 v[104:105], v[104:105], v[108:109]
	v_pk_mul_f32 v[106:107], v[106:107], v[110:111]
	v_pk_mul_f32 v[96:97], v[96:97], v[100:101]
	v_pk_mul_f32 v[98:99], v[98:99], v[102:103]
	v_cvt_pk_bf16_f32 v108, v104, v105
	v_cvt_pk_bf16_f32 v109, v106, v107
	v_cvt_pk_bf16_f32 v110, v96, v97
	v_cvt_pk_bf16_f32 v111, v98, v99
	global_store_dwordx4 v[208:209], v[108:111], off
	v_pk_mul_f32 v[92:93], v[92:93], v[234:235] op_sel_hi:[1,0]
	v_pk_mul_f32 v[94:95], v[94:95], v[234:235] op_sel_hi:[1,0]
	v_pk_mul_f32 v[84:85], v[84:85], v[234:235] op_sel_hi:[1,0]
	v_pk_mul_f32 v[86:87], v[86:87], v[234:235] op_sel_hi:[1,0]
	v_exp_f32_e32 v92, v92
	v_exp_f32_e32 v93, v93
	v_exp_f32_e32 v94, v94
	v_exp_f32_e32 v95, v95
	v_exp_f32_e32 v84, v84
	v_exp_f32_e32 v85, v85
	v_exp_f32_e32 v86, v86
	v_exp_f32_e32 v87, v87
	v_pk_mul_f32 v[88:89], v[88:89], v[234:235] op_sel:[0,1] op_sel_hi:[1,1]
	v_pk_mul_f32 v[90:91], v[90:91], v[234:235] op_sel:[0,1] op_sel_hi:[1,1]
	v_pk_mul_f32 v[80:81], v[80:81], v[234:235] op_sel:[0,1] op_sel_hi:[1,1]
	v_pk_mul_f32 v[82:83], v[82:83], v[234:235] op_sel:[0,1] op_sel_hi:[1,1]
	v_pk_add_f32 v[92:93], v[92:93], 1.0 op_sel_hi:[1,0]
	v_pk_add_f32 v[94:95], v[94:95], 1.0 op_sel_hi:[1,0]
	v_pk_add_f32 v[84:85], v[84:85], 1.0 op_sel_hi:[1,0]
	v_pk_add_f32 v[86:87], v[86:87], 1.0 op_sel_hi:[1,0]
	v_rcp_f32_e32 v92, v92
	v_rcp_f32_e32 v93, v93
	v_rcp_f32_e32 v94, v94
	v_rcp_f32_e32 v95, v95
	v_rcp_f32_e32 v84, v84
	v_rcp_f32_e32 v85, v85
	v_rcp_f32_e32 v86, v86
	v_rcp_f32_e32 v87, v87
	v_mad_i64_i32 v[208:209], s[4:5], v158, s68, v[220:221]
	v_lshl_add_u64 v[208:209], v[208:209], 0, v[250:251]
	v_pk_mul_f32 v[88:89], v[88:89], v[92:93]
	v_pk_mul_f32 v[90:91], v[90:91], v[94:95]
	v_pk_mul_f32 v[80:81], v[80:81], v[84:85]
	v_pk_mul_f32 v[82:83], v[82:83], v[86:87]
	v_cvt_pk_bf16_f32 v92, v88, v89
	v_cvt_pk_bf16_f32 v93, v90, v91
	v_cvt_pk_bf16_f32 v94, v80, v81
	v_cvt_pk_bf16_f32 v95, v82, v83
	global_store_dwordx4 v[208:209], v[92:95], off
	v_pk_mul_f32 v[76:77], v[76:77], v[184:185] op_sel_hi:[1,0]
	v_pk_mul_f32 v[78:79], v[78:79], v[184:185] op_sel_hi:[1,0]
	v_pk_mul_f32 v[68:69], v[68:69], v[184:185] op_sel_hi:[1,0]
	v_pk_mul_f32 v[70:71], v[70:71], v[184:185] op_sel_hi:[1,0]
	v_exp_f32_e32 v76, v76
	v_exp_f32_e32 v77, v77
	v_exp_f32_e32 v78, v78
	v_exp_f32_e32 v79, v79
	v_exp_f32_e32 v68, v68
	v_exp_f32_e32 v69, v69
	v_exp_f32_e32 v70, v70
	v_exp_f32_e32 v71, v71
	v_pk_mul_f32 v[72:73], v[72:73], v[184:185] op_sel:[0,1] op_sel_hi:[1,1]
	v_pk_mul_f32 v[74:75], v[74:75], v[184:185] op_sel:[0,1] op_sel_hi:[1,1]
; __device__ __forceinline__ unsigned cvt_pk_bf16(float lo, float hi) { unsigned r; asm volatile("v_cvt_pk_bf16_f32 %0, %1, %2" : "=v"(r) : "v"(lo), "v"(hi)); return r; }
; __device__ __forceinline__ float fast_rcp(float x) { return __builtin_amdgcn_rcpf(x); }
; __device__ __forceinline__ unsigned cvt_pk_bf16(float lo, float hi) { const f32x2 v = {lo, hi}; const bf16x2_t b = __builtin_convertvector(v, bf16x2_t); return __builtin_bit_cast(unsigned, b); }
;     __device__ __forceinline__ void operator()(const f32x4 (&acc)[2][2][4][2], const Unit& u, int wr, int wc, int fr, int fq) const {
;     ...
;             for (int m = 0; m < 4; ++m) {
;                 const int r = row0 + ai * HALF + m * 16; const float rs = rsv[ai][m], nrs = rs * -1.4426950408889634f, rs2 = rs * rs;
;                 float o[8];
; #pragma unroll
;                 for (int n = 0; n < 2; ++n) {
;                     const f32x4 t = acc[ai][0][m][n] * nrs, p = (acc[ai][0][m][n] * acc[ai][1][m][n]) * rs2;
; #pragma unroll
;                     for (int j = 0; j < 4; ++j) o[4 * n + j] = p[j] * fast_rcp(1.0f + __builtin_amdgcn_exp2f(t[j]));
;                 }
;                 u32x4 w; w.x = cvt_pk_bf16(o[0], o[1]); w.y = cvt_pk_bf16(o[2], o[3]); w.z = cvt_pk_bf16(o[4], o[5]); w.w = cvt_pk_bf16(o[6], o[7]);
;                 *(u32x4*)(O + (size_t)r * ldo + col0) = w;
	v_pk_mul_f32 v[64:65], v[64:65], v[184:185] op_sel:[0,1] op_sel_hi:[1,1]
	v_pk_mul_f32 v[66:67], v[66:67], v[184:185] op_sel:[0,1] op_sel_hi:[1,1]
	v_pk_add_f32 v[76:77], v[76:77], 1.0 op_sel_hi:[1,0]
	v_pk_add_f32 v[78:79], v[78:79], 1.0 op_sel_hi:[1,0]
	v_pk_add_f32 v[68:69], v[68:69], 1.0 op_sel_hi:[1,0]
	v_pk_add_f32 v[70:71], v[70:71], 1.0 op_sel_hi:[1,0]
	v_rcp_f32_e32 v76, v76
	v_rcp_f32_e32 v77, v77
	v_rcp_f32_e32 v78, v78
	v_rcp_f32_e32 v79, v79
	v_rcp_f32_e32 v68, v68
	v_rcp_f32_e32 v69, v69
	v_rcp_f32_e32 v70, v70
	v_rcp_f32_e32 v71, v71
	v_mad_i64_i32 v[208:209], s[4:5], v156, s68, v[220:221]
	v_lshl_add_u64 v[208:209], v[208:209], 0, v[250:251]
	v_pk_mul_f32 v[72:73], v[72:73], v[76:77]
	v_pk_mul_f32 v[74:75], v[74:75], v[78:79]
	v_pk_mul_f32 v[64:65], v[64:65], v[68:69]
	v_pk_mul_f32 v[66:67], v[66:67], v[70:71]
	v_cvt_pk_bf16_f32 v76, v72, v73
	v_cvt_pk_bf16_f32 v77, v74, v75
	v_cvt_pk_bf16_f32 v78, v64, v65
	v_cvt_pk_bf16_f32 v79, v66, v67
	global_store_dwordx4 v[208:209], v[76:79], off
	v_pk_mul_f32 v[60:61], v[60:61], v[186:187] op_sel_hi:[1,0]
	v_pk_mul_f32 v[62:63], v[62:63], v[186:187] op_sel_hi:[1,0]
	v_pk_mul_f32 v[52:53], v[52:53], v[186:187] op_sel_hi:[1,0]
	v_pk_mul_f32 v[54:55], v[54:55], v[186:187] op_sel_hi:[1,0]
	v_exp_f32_e32 v60, v60
	v_exp_f32_e32 v61, v61
	v_exp_f32_e32 v62, v62
	v_exp_f32_e32 v63, v63
	v_exp_f32_e32 v52, v52
	v_exp_f32_e32 v53, v53
	v_exp_f32_e32 v54, v54
	v_exp_f32_e32 v55, v55
	v_pk_mul_f32 v[56:57], v[56:57], v[186:187] op_sel:[0,1] op_sel_hi:[1,1]
	v_pk_mul_f32 v[58:59], v[58:59], v[186:187] op_sel:[0,1] op_sel_hi:[1,1]
	v_pk_mul_f32 v[48:49], v[48:49], v[186:187] op_sel:[0,1] op_sel_hi:[1,1]
	v_pk_mul_f32 v[50:51], v[50:51], v[186:187] op_sel:[0,1] op_sel_hi:[1,1]
	v_pk_add_f32 v[60:61], v[60:61], 1.0 op_sel_hi:[1,0]
	v_pk_add_f32 v[62:63], v[62:63], 1.0 op_sel_hi:[1,0]
	v_pk_add_f32 v[52:53], v[52:53], 1.0 op_sel_hi:[1,0]
	v_pk_add_f32 v[54:55], v[54:55], 1.0 op_sel_hi:[1,0]
	v_rcp_f32_e32 v60, v60
	v_rcp_f32_e32 v61, v61
	v_rcp_f32_e32 v62, v62
	v_rcp_f32_e32 v63, v63
	v_rcp_f32_e32 v52, v52
	v_rcp_f32_e32 v53, v53
	v_rcp_f32_e32 v54, v54
	v_rcp_f32_e32 v55, v55
	v_mad_i64_i32 v[208:209], s[4:5], v154, s68, v[220:221]
	v_lshl_add_u64 v[208:209], v[208:209], 0, v[250:251]
	v_pk_mul_f32 v[56:57], v[56:57], v[60:61]
	v_pk_mul_f32 v[58:59], v[58:59], v[62:63]
	v_pk_mul_f32 v[48:49], v[48:49], v[52:53]
	v_pk_mul_f32 v[50:51], v[50:51], v[54:55]
	v_cvt_pk_bf16_f32 v60, v56, v57
	v_cvt_pk_bf16_f32 v61, v58, v59
	v_cvt_pk_bf16_f32 v62, v48, v49
	v_cvt_pk_bf16_f32 v63, v50, v51
	global_store_dwordx4 v[208:209], v[60:63], off
	v_pk_mul_f32 v[44:45], v[44:45], v[188:189] op_sel_hi:[1,0]
	v_pk_mul_f32 v[46:47], v[46:47], v[188:189] op_sel_hi:[1,0]
	v_pk_mul_f32 v[36:37], v[36:37], v[188:189] op_sel_hi:[1,0]
	v_pk_mul_f32 v[38:39], v[38:39], v[188:189] op_sel_hi:[1,0]
	v_exp_f32_e32 v44, v44
	v_exp_f32_e32 v45, v45
	v_exp_f32_e32 v46, v46
	v_exp_f32_e32 v47, v47
	v_exp_f32_e32 v36, v36
	v_exp_f32_e32 v37, v37
	v_exp_f32_e32 v38, v38
	v_exp_f32_e32 v39, v39
	v_pk_mul_f32 v[40:41], v[40:41], v[188:189] op_sel:[0,1] op_sel_hi:[1,1]
	v_pk_mul_f32 v[42:43], v[42:43], v[188:189] op_sel:[0,1] op_sel_hi:[1,1]
	v_pk_mul_f32 v[32:33], v[32:33], v[188:189] op_sel:[0,1] op_sel_hi:[1,1]
	v_pk_mul_f32 v[34:35], v[34:35], v[188:189] op_sel:[0,1] op_sel_hi:[1,1]
	v_pk_add_f32 v[44:45], v[44:45], 1.0 op_sel_hi:[1,0]
	v_pk_add_f32 v[46:47], v[46:47], 1.0 op_sel_hi:[1,0]
	v_pk_add_f32 v[36:37], v[36:37], 1.0 op_sel_hi:[1,0]
	v_pk_add_f32 v[38:39], v[38:39], 1.0 op_sel_hi:[1,0]
	v_rcp_f32_e32 v44, v44
	v_rcp_f32_e32 v45, v45
	v_rcp_f32_e32 v46, v46
	v_rcp_f32_e32 v47, v47
	v_rcp_f32_e32 v36, v36
	v_rcp_f32_e32 v37, v37
	v_rcp_f32_e32 v38, v38
; __device__ __forceinline__ unsigned cvt_pk_bf16(float lo, float hi) { unsigned r; asm volatile("v_cvt_pk_bf16_f32 %0, %1, %2" : "=v"(r) : "v"(lo), "v"(hi)); return r; }
; __device__ __forceinline__ float fast_rcp(float x) { return __builtin_amdgcn_rcpf(x); }
; #define PG8_BAR __builtin_amdgcn_s_barrier()
; __device__ __forceinline__ unsigned cvt_pk_bf16(float lo, float hi) { const f32x2 v = {lo, hi}; const bf16x2_t b = __builtin_convertvector(v, bf16x2_t); return __builtin_bit_cast(unsigned, b); }
;     __device__ __forceinline__ void operator()(const f32x4 (&acc)[2][2][4][2], const Unit& u, int wr, int wc, int fr, int fq) const {
;     ...
;             for (int m = 0; m < 4; ++m) {
;                 const int r = row0 + ai * HALF + m * 16; const float rs = rsv[ai][m], nrs = rs * -1.4426950408889634f, rs2 = rs * rs;
;                 float o[8];
; #pragma unroll
;                 for (int n = 0; n < 2; ++n) {
;                     const f32x4 t = acc[ai][0][m][n] * nrs, p = (acc[ai][0][m][n] * acc[ai][1][m][n]) * rs2;
; #pragma unroll
;                     for (int j = 0; j < 4; ++j) o[4 * n + j] = p[j] * fast_rcp(1.0f + __builtin_amdgcn_exp2f(t[j]));
;                 }
;                 u32x4 w; w.x = cvt_pk_bf16(o[0], o[1]); w.y = cvt_pk_bf16(o[2], o[3]); w.z = cvt_pk_bf16(o[4], o[5]); w.w = cvt_pk_bf16(o[6], o[7]);
;                 *(u32x4*)(O + (size_t)r * ldo + col0) = w;
; template <class Epi, class Sched, bool ALIGN_EPI = false, bool SP2 = false>
; __device__ __forceinline__ void gemm_phase(PG8_LAS unsigned char* lds, const Gemm g, const Sched& S, const Epi& E) {
;     ...
;         if constexpr (!Epi::AFTER_DRAIN) { E(acc, cur, wr, wc, fr, fq); S.done(cur); }
;         if (!has_next) break;
; #pragma unroll
;         for (int a = 0; a < 2; ++a)
; #pragma unroll
;             for (int b = 0; b < 2; ++b)
; #pragma unroll
;                 for (int m = 0; m < 4; ++m)
; #pragma unroll
;                     for (int n = 0; n < 2; ++n) acc[a][b][m][n] = (f32x4){0.f, 0.f, 0.f, 0.f};
;         cur = nxt; cA = nA; cB = nB; ++ui;
;         if constexpr (ALIGN_EPI) { if (wr == 1) PG8_BAR; }
	v_rcp_f32_e32 v39, v39
	v_mad_i64_i32 v[208:209], s[4:5], v152, s68, v[220:221]
	v_lshl_add_u64 v[208:209], v[208:209], 0, v[250:251]
	v_pk_mul_f32 v[40:41], v[40:41], v[44:45]
	v_pk_mul_f32 v[42:43], v[42:43], v[46:47]
	v_pk_mul_f32 v[32:33], v[32:33], v[36:37]
	v_pk_mul_f32 v[34:35], v[34:35], v[38:39]
	v_cvt_pk_bf16_f32 v44, v40, v41
	v_cvt_pk_bf16_f32 v45, v42, v43
	v_cvt_pk_bf16_f32 v46, v32, v33
	v_cvt_pk_bf16_f32 v47, v34, v35
	global_store_dwordx4 v[208:209], v[44:47], off
	v_pk_mul_f32 v[28:29], v[28:29], v[190:191] op_sel_hi:[1,0]
	v_pk_mul_f32 v[30:31], v[30:31], v[190:191] op_sel_hi:[1,0]
	v_pk_mul_f32 v[20:21], v[20:21], v[190:191] op_sel_hi:[1,0]
	v_pk_mul_f32 v[22:23], v[22:23], v[190:191] op_sel_hi:[1,0]
	v_exp_f32_e32 v28, v28
	v_exp_f32_e32 v29, v29
	v_exp_f32_e32 v30, v30
	v_exp_f32_e32 v31, v31
	v_exp_f32_e32 v20, v20
	v_exp_f32_e32 v21, v21
	v_exp_f32_e32 v22, v22
	v_exp_f32_e32 v23, v23
	v_pk_mul_f32 v[24:25], v[24:25], v[190:191] op_sel:[0,1] op_sel_hi:[1,1]
	v_pk_mul_f32 v[26:27], v[26:27], v[190:191] op_sel:[0,1] op_sel_hi:[1,1]
	v_pk_mul_f32 v[16:17], v[16:17], v[190:191] op_sel:[0,1] op_sel_hi:[1,1]
	v_pk_mul_f32 v[18:19], v[18:19], v[190:191] op_sel:[0,1] op_sel_hi:[1,1]
	v_pk_add_f32 v[28:29], v[28:29], 1.0 op_sel_hi:[1,0]
	v_pk_add_f32 v[30:31], v[30:31], 1.0 op_sel_hi:[1,0]
	v_pk_add_f32 v[20:21], v[20:21], 1.0 op_sel_hi:[1,0]
	v_pk_add_f32 v[22:23], v[22:23], 1.0 op_sel_hi:[1,0]
	v_rcp_f32_e32 v28, v28
	v_rcp_f32_e32 v29, v29
	v_rcp_f32_e32 v30, v30
	v_rcp_f32_e32 v31, v31
	v_rcp_f32_e32 v20, v20
	v_rcp_f32_e32 v21, v21
	v_rcp_f32_e32 v22, v22
	v_rcp_f32_e32 v23, v23
	v_mad_i64_i32 v[208:209], s[4:5], v150, s68, v[220:221]
	v_lshl_add_u64 v[208:209], v[208:209], 0, v[250:251]
	v_pk_mul_f32 v[24:25], v[24:25], v[28:29]
	v_pk_mul_f32 v[26:27], v[26:27], v[30:31]
	v_pk_mul_f32 v[16:17], v[16:17], v[20:21]
	v_pk_mul_f32 v[18:19], v[18:19], v[22:23]
	v_cvt_pk_bf16_f32 v28, v24, v25
	v_cvt_pk_bf16_f32 v29, v26, v27
	v_cvt_pk_bf16_f32 v30, v16, v17
	v_cvt_pk_bf16_f32 v31, v18, v19
	global_store_dwordx4 v[208:209], v[28:31], off
	v_pk_mul_f32 v[12:13], v[12:13], v[204:205] op_sel_hi:[1,0]
	v_pk_mul_f32 v[14:15], v[14:15], v[204:205] op_sel_hi:[1,0]
	v_pk_mul_f32 v[4:5], v[4:5], v[204:205] op_sel_hi:[1,0]
	v_pk_mul_f32 v[6:7], v[6:7], v[204:205] op_sel_hi:[1,0]
	v_exp_f32_e32 v12, v12
	v_exp_f32_e32 v13, v13
	v_exp_f32_e32 v14, v14
	v_exp_f32_e32 v15, v15
	v_exp_f32_e32 v4, v4
	v_exp_f32_e32 v5, v5
	v_exp_f32_e32 v6, v6
	v_exp_f32_e32 v7, v7
	v_pk_mul_f32 v[8:9], v[8:9], v[204:205] op_sel:[0,1] op_sel_hi:[1,1]
	v_pk_mul_f32 v[10:11], v[10:11], v[204:205] op_sel:[0,1] op_sel_hi:[1,1]
	v_pk_mul_f32 v[0:1], v[0:1], v[204:205] op_sel:[0,1] op_sel_hi:[1,1]
	v_pk_mul_f32 v[2:3], v[2:3], v[204:205] op_sel:[0,1] op_sel_hi:[1,1]
	v_pk_add_f32 v[12:13], v[12:13], 1.0 op_sel_hi:[1,0]
	v_pk_add_f32 v[14:15], v[14:15], 1.0 op_sel_hi:[1,0]
	v_pk_add_f32 v[4:5], v[4:5], 1.0 op_sel_hi:[1,0]
	v_pk_add_f32 v[6:7], v[6:7], 1.0 op_sel_hi:[1,0]
	v_rcp_f32_e32 v12, v12
	v_rcp_f32_e32 v13, v13
	v_rcp_f32_e32 v14, v14
	v_rcp_f32_e32 v15, v15
	v_rcp_f32_e32 v4, v4
	v_rcp_f32_e32 v5, v5
	v_rcp_f32_e32 v6, v6
	v_rcp_f32_e32 v7, v7
	v_mad_i64_i32 v[208:209], s[4:5], v148, s68, v[220:221]
	v_lshl_add_u64 v[208:209], v[208:209], 0, v[250:251]
	v_pk_mul_f32 v[8:9], v[8:9], v[12:13]
	v_pk_mul_f32 v[10:11], v[10:11], v[14:15]
	v_pk_mul_f32 v[0:1], v[0:1], v[4:5]
	v_pk_mul_f32 v[2:3], v[2:3], v[6:7]
	v_cvt_pk_bf16_f32 v12, v8, v9
	v_cvt_pk_bf16_f32 v13, v10, v11
	v_cvt_pk_bf16_f32 v14, v0, v1
	v_cvt_pk_bf16_f32 v15, v2, v3
	global_store_dwordx4 v[208:209], v[12:15], off
	s_cbranch_vccnz .LBB0_255
	s_andn2_b64 vcc, exec, s[16:17]
	s_cbranch_vccnz .LBB0_254
	s_barrier
	s_branch .LBB0_254

; #define PG8_WAIT_V(n) asm volatile("s_waitcnt vmcnt(" #n ")" ::: "memory")
; template <class Epi, class Sched, bool ALIGN_EPI = false, bool SP2 = false>
; __device__ __forceinline__ void gemm_phase(PG8_LAS unsigned char* lds, const Gemm g, const Sched& S, const Epi& E) {
;     int tid_ = threadIdx.x; asm volatile("" : "+v"(tid_));
;     const int tid = tid_, wid = __builtin_amdgcn_readfirstlane(tid >> 6), lane = tid & 63, wr = wid >> 2, wc = wid & 3, fr = lane & 15, fq = lane >> 4;
;     int K_ = g.K; asm volatile("" : "+s"(K_));
;     const int K = K_, nt = K / BK;
;     unsigned voffA[2], voffB[2];
; #pragma unroll
;     for (int i = 0; i < 2; ++i) { int R, C; stage_rc(tid * 16 + i * 8192, R, C); const int Rb = Epi::PERM ? ((R & ~31) + perm32(R & 31)) : R;
;         voffA[i] = (unsigned)(R * K + C) * 2u; voffB[i] = (unsigned)(Rb * K + C) * 2u; }
;     const size_t kstep = (size_t)(BK * 2);
;     const size_t hstep = (size_t)HALF * K * 2;
;     const size_t tstep = 2 * hstep;
;     const unsigned ldsw = (unsigned)wid * 1024u;
;     const int aoff = lds_byte(wr * 64 + fr, fq * 8), boff = lds_byte(wc * 32 + fr, fq * 8);
;     ...
;     Unit cur, nxt; int ui = 0;
;     if (!S.next(0, cur)) return;
;     f32x4 acc[2][2][4][2];
; #pragma unroll
;     for (int a = 0; a < 2; ++a)
; #pragma unroll
;         for (int b = 0; b < 2; ++b)
; #pragma unroll
;             for (int m = 0; m < 4; ++m)
; #pragma unroll
;                 for (int n = 0; n < 2; ++n) acc[a][b][m][n] = (f32x4){0.f, 0.f, 0.f, 0.f};
;     bf16x8 At[4][2], B0[2][2], B1[2][2];
;     const char* cA = (const char*)g.A + (size_t)cur.pm * tstep; const char* cB = (const char*)g.Bt + (size_t)cur.pn * tstep;
;     S.a_ready(cur);
;     if constexpr (SP2) {
;         PG8_STAGE(PG8_SB(0, 0), cB, voffB); PG8_STAGE(PG8_SB(0, 1), cB + hstep, voffB); PG8_STAGE(PG8_SA(0, 0), cA, voffA); PG8_STAGE(PG8_SA(0, 1), cA + hstep, voffA);
;         if (wr == 1) PG8_BAR;
;         PG8_WAIT_V(2); PG8_BAR;
;         PG8_STAGE(PG8_SB(1, 0), cB + kstep, voffB); PG8_STAGE(PG8_SA(1, 0), cA + kstep, voffA); PG8_STAGE(PG8_SB(1, 1), cB + hstep + kstep, voffB);
; __global__ void __launch_bounds__(NWAVES * 64, 2) fwd_megakernel(Args args) {
;     ...
;     if (IN(6)) {
;         pg8::Gemm g{XG, (const bf16*)(ws + WS_W2T), MT, 2 * FF, D}; pg8::StaticOrder S; S.init(MT, 2 * FF, F.G, (int)blockIdx.x);
;         pg8::EpiAct E{ACT, SS, FF};
.LBB0_999:
	s_cmp_lt_i32 s28, 7
	s_cselect_b64 s[4:5], -1, 0
	s_and_b64 s[8:9], s[4:5], s[0:1]
	s_andn2_b64 vcc, exec, s[8:9]
	s_cbranch_vccnz .LBB0_1041
	s_mov_b32 s86, -1
	v_lshlrev_b32_e32 v236, 4, v192
	v_mov_b32_e32 v237, 0
	v_lshl_add_u64 v[236:237], s[44:45], 0, v[236:237]
	v_mov_b32_e32 v12, v192
	s_movk_i32 s0, 0x400
	v_readfirstlane_b32 s7, v12
	s_cmpk_gt_i32 s2, 0x5d7
	s_cbranch_scc1 .LBB0_1021
	v_lshlrev_b32_e32 v0, 4, v12
	v_add_u32_e32 v1, 0x2000, v0
	s_waitcnt lgkmcnt(0)
	v_ashrrev_i32_e32 v2, 31, v1
	v_lshrrev_b32_e32 v2, 22, v2
	v_add_u32_e32 v2, v1, v2
	v_ashrrev_i32_e32 v2, 10, v2
	v_mul_i32_i24_e32 v3, 0x400, v2
	v_sub_u32_e32 v1, v1, v3
	v_lshrrev_b32_e32 v3, 4, v1
	v_bitop3_b32 v1, v3, v1, 32 bitop3:0x6c
	v_ashrrev_i32_e32 v3, 31, v1
	v_lshrrev_b32_e32 v3, 26, v3
	v_add_u32_e32 v3, v1, v3
	v_lshlrev_b32_e32 v5, 3, v2
	v_ashrrev_i32_e32 v4, 6, v3
	v_and_b32_e32 v5, -16, v5
	v_lshlrev_b32_e32 v2, 5, v2
	v_add_u32_e32 v5, v4, v5
	v_and_b32_e32 v13, 32, v2
	v_and_b32_e32 v2, 0xc0, v3
	v_and_b32_e32 v4, 3, v4
	s_mov_b32 s4, 0x7fffffe0
	v_lshrrev_b32_e32 v6, 2, v5
	v_lshlrev_b32_e32 v7, 1, v5
	v_sub_u32_e32 v1, v1, v2
	v_mov_b32_e32 v2, 1
	v_and_or_b32 v4, v5, s4, v4
	v_and_b32_e32 v6, 4, v6
	v_and_b32_e32 v7, 24, v7
	v_ashrrev_i16_sdwa v1, v2, sext(v1) dst_sel:DWORD dst_unused:UNUSED_PAD src0_sel:DWORD src1_sel:BYTE_0
	v_or3_b32 v4, v4, v6, v7
	v_bfe_i32 v14, v1, 0, 16
	v_mul_lo_u32 v4, v4, s0
	v_add_u32_e32 v1, v13, v14
	v_mul_lo_u32 v15, v5, s0
	v_add_lshl_u32 v128, v4, v1, 1
	v_add_lshl_u32 v130, v1, v15, 1
	v_bfe_i32 v1, v12, 27, 1
	v_lshrrev_b32_e32 v1, 22, v1
	v_add_u32_e32 v1, v0, v1
	v_and_b32_e32 v1, 0xfffffc00, v1
	v_sub_u32_e32 v0, v0, v1
	v_lshrrev_b32_e32 v1, 4, v0
	v_ashrrev_i32_e32 v4, 31, v12
	v_bitop3_b32 v0, v1, v0, 32 bitop3:0x6c
	v_lshrrev_b32_e32 v4, 26, v4
	v_ashrrev_i32_e32 v1, 31, v0
	v_add_u32_e32 v4, v12, v4
	v_lshrrev_b32_e32 v1, 26, v1
	v_ashrrev_i32_e32 v4, 6, v4
	v_add_u32_e32 v1, v0, v1
	v_lshlrev_b32_e32 v5, 3, v4
	s_add_u32 s3, s26, 0x1600000
	v_ashrrev_i32_e32 v3, 6, v1
	v_and_b32_e32 v5, -16, v5
	s_addc_u32 s40, s27, 0
	v_add_u32_e32 v5, v3, v5
	v_and_b32_e32 v3, 3, v3
	s_ashr_i32 s42, s2, 31
	v_and_or_b32 v3, v5, s4, v3
	s_lshr_b32 s4, s42, 29
	s_add_i32 s4, s2, s4
	s_ashr_i32 s18, s7, 6
	s_ashr_i32 s1, s0, 31
	s_ashr_i32 s5, s4, 3
	s_and_b32 s4, s4, -8
	s_ashr_i32 s19, s7, 8
	s_lshl_b64 s[10:11], s[0:1], 8
	s_lshl_b64 s[12:13], s[0:1], 9
	s_lshl_b32 s41, s18, 10
	s_sub_i32 s4, s2, s4
	s_cmp_lt_i32 s4, 0
	s_movk_i32 s43, 0xbc
	s_cselect_b32 s6, s43, 0xbb
	s_mul_i32 s4, s4, s6
	s_add_i32 s4, s4, s5
	s_mul_hi_i32 s5, s4, 0x2e8ba2e9
	s_lshr_b32 s6, s5, 31
	s_ashr_i32 s5, s5, 5
	v_and_b32_e32 v1, 0xc0, v1
	s_add_i32 s5, s5, s6
	v_lshrrev_b32_e32 v6, 2, v5
	v_lshlrev_b32_e32 v7, 1, v5
	v_sub_u32_e32 v0, v0, v1
	s_lshl_b32 s14, s5, 3
	v_and_b32_e32 v6, 4, v6
	v_and_b32_e32 v7, 24, v7
	v_lshlrev_b32_e32 v4, 5, v4
	v_ashrrev_i16_sdwa v0, v2, sext(v0) dst_sel:DWORD dst_unused:UNUSED_PAD src0_sel:DWORD src1_sel:BYTE_0
	s_sub_i32 s6, 0x44, s14
	s_mulk_i32 s5, 0xb0
	v_or3_b32 v3, v3, v6, v7
	v_and_b32_e32 v16, 32, v4
	v_bfe_i32 v17, v0, 0, 16
	s_min_u32 s15, s6, 8
	s_sub_i32 s16, s4, s5
	v_mul_lo_u32 v3, v3, s0
	v_add_u32_e32 v0, v16, v17
	s_sext_i32_i16 s4, s16
	v_cvt_f32_ubyte0_e32 v2, s15
	v_add_lshl_u32 v132, v3, v0, 1
	v_cvt_f32_i32_e32 v1, s4
	v_rcp_iflag_f32_e32 v3, v2
	v_mul_lo_u32 v18, v5, s0
	v_add_lshl_u32 v134, v0, v18, 1
	s_ashr_i32 s4, s4, 30
	v_mul_f32_e32 v0, v1, v3
	v_trunc_f32_e32 v0, v0
	v_fma_f32 v1, -v0, v2, v1
	v_cvt_i32_f32_e32 v0, v0
	s_or_b32 s6, s4, 1
	v_cmp_ge_f32_e64 s[4:5], |v1|, v2
	s_and_b64 s[4:5], s[4:5], exec
	s_cselect_b32 s4, s6, 0
	v_readfirstlane_b32 s5, v0
	s_add_i32 s6, s5, s4
	s_mul_i32 s4, s6, s15
	s_sub_i32 s4, s16, s4
	s_sext_i32_i16 s4, s4
	s_add_i32 s4, s14, s4
	s_ashr_i32 s5, s4, 31
	s_mul_i32 s5, s12, s5
	s_mul_hi_u32 s14, s12, s4
	s_add_i32 s5, s14, s5
	s_lshr_b64 s[14:15], s[0:1], 23
	s_mul_i32 s15, s14, s4
	s_bfe_i64 s[16:17], s[6:7], 0x100000
	s_add_i32 s5, s5, s15
	s_mul_i32 s15, s12, s17
	s_mul_hi_u32 s17, s12, s16
	s_add_i32 s15, s17, s15
	s_mul_i32 s14, s14, s16
	s_add_i32 s15, s15, s14
	s_mul_i32 s14, s12, s16
	s_add_u32 s38, s3, s14
	s_addc_u32 s39, s40, s15
	s_add_i32 s48, s41, 0
	s_add_i32 m0, s48, 0x10000
	s_mul_i32 s20, s12, s4
	global_load_lds_dwordx4 v132, s[38:39]
	s_add_i32 m0, s48, 0x12000
	s_add_u32 s14, s38, s10
	global_load_lds_dwordx4 v128, s[38:39]
	s_addc_u32 s15, s39, s11
	s_add_i32 m0, s48, 0x14000
	v_mov_b32_e32 v133, 0
	global_load_lds_dwordx4 v132, s[14:15]
	s_add_i32 m0, s48, 0x16000
	s_add_u32 s36, s34, s20
	s_addc_u32 s37, s35, s5
	s_add_i32 s49, s48, 0x2000
	global_load_lds_dwordx4 v128, s[14:15]
	s_mov_b32 m0, s48
	s_add_u32 s16, s36, s10
	global_load_lds_dwordx4 v134, s[36:37]
	s_mov_b32 m0, s49
	s_addc_u32 s17, s37, s11
	s_add_i32 s56, s48, 0x4000
	global_load_lds_dwordx4 v130, s[36:37]
	s_mov_b32 m0, s56
	s_add_i32 s57, s48, 0x6000
	global_load_lds_dwordx4 v134, s[16:17]
	s_mov_b32 m0, s57
	v_mov_b32_e32 v129, v133
	global_load_lds_dwordx4 v130, s[16:17]
	v_mov_b32_e32 v135, v133
	v_mov_b32_e32 v131, v133
	s_cmp_eq_u32 s19, 1
	s_mov_b32 s58, 0
	v_lshl_add_u64 v[8:9], s[38:39], 0, v[132:133]
	v_lshl_add_u64 v[4:5], s[38:39], 0, v[128:129]
	v_lshl_add_u64 v[2:3], s[14:15], 0, v[132:133]
	v_lshl_add_u64 v[0:1], s[14:15], 0, v[128:129]
	v_lshl_add_u64 v[6:7], s[36:37], 0, v[134:135]
	s_cselect_b64 s[14:15], -1, 0
	s_cmp_lg_u32 s19, 1
	v_lshl_add_u64 v[10:11], s[36:37], 0, v[130:131]
	s_cbranch_scc1 .LBB0_1003
	s_barrier

; __device__ __forceinline__ void row_rs8(const float* SS, int row0, int fq, float (&rsv)[2][4]) {
;     f32x4 q[2][4];
; #pragma unroll
;     for (int ai = 0; ai < 2; ++ai)
; #pragma unroll
;         for (int m = 0; m < 4; ++m) q[ai][m] = *(const f32x4*)(SS + (size_t)(row0 + ai * HALF + m * 16) * 16 + 4 * fq);
; #pragma unroll
;     for (int ai = 0; ai < 2; ++ai)
; #pragma unroll
;         for (int m = 0; m < 4; ++m) { float t = (q[ai][m][0] + q[ai][m][1]) + (q[ai][m][2] + q[ai][m][3]); t += __shfl_xor(t, 16); t += __shfl_xor(t, 32); rsv[ai][m] = __builtin_amdgcn_rsqf(t * (1.0f / 1024.0f) + 1e-6f); }
; }
;     __device__ __forceinline__ void operator()(const f32x4 (&acc)[2][2][4][2], const Unit& u, int wr, int wc, int fr, int fq) const {
;         const int row0 = u.pm * BM + wr * 64 + fr, col0 = u.pn * HALF + wc * 32 + 8 * fq;
;         float rsv[2][4]; row_rs8(SS, row0, fq, rsv);
; #pragma unroll
;         for (int ai = 0; ai < 2; ++ai)
; #pragma unroll
;             for (int m = 0; m < 4; ++m) {
;                 const int r = row0 + ai * HALF + m * 16; const float rs = rsv[ai][m], nrs = rs * -1.4426950408889634f, rs2 = rs * rs;
.LBB0_1017:
	v_lshl_add_u32 v162, s4, 8, v164
	v_or_b32_e32 v160, 16, v162
	v_or_b32_e32 v158, 32, v162
	v_or_b32_e32 v156, 48, v162
	v_add_u32_e32 v154, 0x80, v162
	v_add_u32_e32 v152, 0x90, v162
	v_add_u32_e32 v150, 0xa0, v162
	v_add_u32_e32 v148, 0xb0, v162
	v_lshl_or_b32 v250, s5, 7, v166
	v_lshlrev_b32_e32 v250, 1, v250
	v_mov_b32_e32 v251, 0
	v_mov_b64_e32 v[220:221], s[52:53]
	s_and_b64 vcc, exec, s[0:1]
	s_mov_b64 s[0:1], -1
	s_cmp_eq_u32 s4, s86
	s_cbranch_scc1 .Lrs_reuse_p6
	s_mov_b32 s86, s4
	v_and_b32_e32 v252, 48, v192
	v_lshl_add_u32 v252, v164, 6, v252
	v_add_u32_e32 v252, 0x20000, v252
	ds_read_b128 v[174:177], v252
	ds_read_b128 v[178:181], v252 offset:1024
	ds_read_b128 v[182:185], v252 offset:2048
	ds_read_b128 v[186:189], v252 offset:3072
	ds_read_b128 v[194:197], v252 offset:8192
	ds_read_b128 v[198:201], v252 offset:9216
	ds_read_b128 v[202:205], v252 offset:10240
	ds_read_b128 v[206:209], v252 offset:11264
	v_xor_b32_e32 v210, 16, v170
	v_xor_b32_e32 v211, 32, v170
	v_lshlrev_b32_e32 v210, 2, v210
	v_lshlrev_b32_e32 v211, 2, v211
	s_waitcnt lgkmcnt(0)
	v_pk_add_f32 v[174:175], v[174:175], v[176:177]
	v_pk_add_f32 v[178:179], v[178:179], v[180:181]
	v_pk_add_f32 v[182:183], v[182:183], v[184:185]
	v_pk_add_f32 v[186:187], v[186:187], v[188:189]
	v_pk_add_f32 v[194:195], v[194:195], v[196:197]
	v_pk_add_f32 v[198:199], v[198:199], v[200:201]
	v_pk_add_f32 v[202:203], v[202:203], v[204:205]
	v_pk_add_f32 v[206:207], v[206:207], v[208:209]
	v_add_f32_e32 v242, v174, v175
	v_add_f32_e32 v243, v178, v179
	v_add_f32_e32 v244, v182, v183
	v_add_f32_e32 v245, v186, v187
	v_add_f32_e32 v246, v194, v195
	v_add_f32_e32 v247, v198, v199
	v_add_f32_e32 v248, v202, v203
	v_add_f32_e32 v249, v206, v207
	ds_bpermute_b32 v222, v210, v242
	ds_bpermute_b32 v223, v210, v243
	ds_bpermute_b32 v224, v210, v244
	ds_bpermute_b32 v225, v210, v245
	ds_bpermute_b32 v226, v210, v246
	ds_bpermute_b32 v227, v210, v247
	ds_bpermute_b32 v228, v210, v248
	ds_bpermute_b32 v229, v210, v249
	s_waitcnt lgkmcnt(7)
	v_add_f32_e32 v242, v242, v222
	s_waitcnt lgkmcnt(6)
	v_add_f32_e32 v243, v243, v223
	s_waitcnt lgkmcnt(5)
	v_add_f32_e32 v244, v244, v224
	s_waitcnt lgkmcnt(4)
	v_add_f32_e32 v245, v245, v225
	s_waitcnt lgkmcnt(3)
	v_add_f32_e32 v246, v246, v226
	s_waitcnt lgkmcnt(2)
	v_add_f32_e32 v247, v247, v227
	s_waitcnt lgkmcnt(1)
	v_add_f32_e32 v248, v248, v228
	s_waitcnt lgkmcnt(0)
	v_add_f32_e32 v249, v249, v229
	ds_bpermute_b32 v222, v211, v242
	ds_bpermute_b32 v223, v211, v243
	ds_bpermute_b32 v224, v211, v244
	ds_bpermute_b32 v225, v211, v245
	ds_bpermute_b32 v226, v211, v246
	ds_bpermute_b32 v227, v211, v247
	ds_bpermute_b32 v228, v211, v248
	ds_bpermute_b32 v229, v211, v249
	s_waitcnt lgkmcnt(7)
	v_add_f32_e32 v242, v242, v222
	s_waitcnt lgkmcnt(6)
	v_add_f32_e32 v243, v243, v223
	s_waitcnt lgkmcnt(5)
	v_add_f32_e32 v244, v244, v224
	s_waitcnt lgkmcnt(4)
	v_add_f32_e32 v245, v245, v225
	s_waitcnt lgkmcnt(3)
	v_add_f32_e32 v246, v246, v226
	s_waitcnt lgkmcnt(2)
	v_add_f32_e32 v247, v247, v227
	s_waitcnt lgkmcnt(1)
	v_add_f32_e32 v248, v248, v228
	s_waitcnt lgkmcnt(0)
	v_add_f32_e32 v249, v249, v229
	v_fmamk_f32 v242, v242, 0x3a800000, v171
	v_fmamk_f32 v243, v243, 0x3a800000, v171
	v_fmamk_f32 v244, v244, 0x3a800000, v171
	v_fmamk_f32 v245, v245, 0x3a800000, v171
	v_fmamk_f32 v246, v246, 0x3a800000, v171
	v_fmamk_f32 v247, v247, 0x3a800000, v171
	v_fmamk_f32 v248, v248, 0x3a800000, v171
	v_fmamk_f32 v249, v249, 0x3a800000, v171
	v_rsq_f32_e32 v242, v242
	v_rsq_f32_e32 v243, v243
	v_rsq_f32_e32 v244, v244
	v_rsq_f32_e32 v245, v245
	v_rsq_f32_e32 v246, v246
	v_rsq_f32_e32 v247, v247
	v_rsq_f32_e32 v248, v248
	v_rsq_f32_e32 v249, v249
.Lrs_reuse_p6:
	v_pk_mul_f32 v[124:125], v[124:125], v[120:121]
	v_pk_mul_f32 v[126:127], v[126:127], v[122:123]
	v_pk_mul_f32 v[112:113], v[112:113], v[116:117]
	v_pk_mul_f32 v[114:115], v[114:115], v[118:119]
	v_pk_mul_f32 v[104:105], v[104:105], v[108:109]
	v_pk_mul_f32 v[106:107], v[106:107], v[110:111]
	v_pk_mul_f32 v[96:97], v[96:97], v[100:101]
	v_pk_mul_f32 v[98:99], v[98:99], v[102:103]
	v_pk_mul_f32 v[88:89], v[88:89], v[92:93]
	v_pk_mul_f32 v[90:91], v[90:91], v[94:95]
	v_pk_mul_f32 v[80:81], v[80:81], v[84:85]
	v_pk_mul_f32 v[82:83], v[82:83], v[86:87]
	v_pk_mul_f32 v[72:73], v[72:73], v[76:77]
	v_pk_mul_f32 v[74:75], v[74:75], v[78:79]
	v_pk_mul_f32 v[64:65], v[64:65], v[68:69]
	v_pk_mul_f32 v[66:67], v[66:67], v[70:71]
	v_pk_mul_f32 v[56:57], v[56:57], v[60:61]
	v_pk_mul_f32 v[58:59], v[58:59], v[62:63]
	v_pk_mul_f32 v[48:49], v[48:49], v[52:53]
	v_pk_mul_f32 v[50:51], v[50:51], v[54:55]
	v_pk_mul_f32 v[40:41], v[40:41], v[44:45]
	v_pk_mul_f32 v[42:43], v[42:43], v[46:47]
	v_pk_mul_f32 v[32:33], v[32:33], v[36:37]
	v_pk_mul_f32 v[34:35], v[34:35], v[38:39]
	v_pk_mul_f32 v[24:25], v[24:25], v[28:29]
	v_pk_mul_f32 v[26:27], v[26:27], v[30:31]
	v_pk_mul_f32 v[16:17], v[16:17], v[20:21]
	v_pk_mul_f32 v[18:19], v[18:19], v[22:23]
	v_pk_mul_f32 v[8:9], v[8:9], v[12:13]
	v_pk_mul_f32 v[10:11], v[10:11], v[14:15]
	v_pk_mul_f32 v[0:1], v[0:1], v[4:5]
	v_pk_mul_f32 v[2:3], v[2:3], v[6:7]
	v_mul_f32_e32 v230, 0xbfb8aa3b, v242
	v_mul_f32_e32 v231, v242, v242
	v_mul_f32_e32 v232, 0xbfb8aa3b, v243
	v_mul_f32_e32 v233, v243, v243
	v_mul_f32_e32 v234, 0xbfb8aa3b, v244
	v_mul_f32_e32 v235, v244, v244
	v_mul_f32_e32 v184, 0xbfb8aa3b, v245
	v_mul_f32_e32 v185, v245, v245
	v_mul_f32_e32 v186, 0xbfb8aa3b, v246
	v_mul_f32_e32 v187, v246, v246
	v_mul_f32_e32 v188, 0xbfb8aa3b, v247
	v_mul_f32_e32 v189, v247, v247
	v_mul_f32_e32 v190, 0xbfb8aa3b, v248
	v_mul_f32_e32 v191, v248, v248
	v_mul_f32_e32 v204, 0xbfb8aa3b, v249
; __device__ __forceinline__ unsigned cvt_pk_bf16(float lo, float hi) { unsigned r; asm volatile("v_cvt_pk_bf16_f32 %0, %1, %2" : "=v"(r) : "v"(lo), "v"(hi)); return r; }
; __device__ __forceinline__ float fast_rcp(float x) { return __builtin_amdgcn_rcpf(x); }
; __device__ __forceinline__ unsigned cvt_pk_bf16(float lo, float hi) { const f32x2 v = {lo, hi}; const bf16x2_t b = __builtin_convertvector(v, bf16x2_t); return __builtin_bit_cast(unsigned, b); }
;     __device__ __forceinline__ void operator()(const f32x4 (&acc)[2][2][4][2], const Unit& u, int wr, int wc, int fr, int fq) const {
;     ...
;             for (int m = 0; m < 4; ++m) {
;                 const int r = row0 + ai * HALF + m * 16; const float rs = rsv[ai][m], nrs = rs * -1.4426950408889634f, rs2 = rs * rs;
;                 float o[8];
; #pragma unroll
;                 for (int n = 0; n < 2; ++n) {
;                     const f32x4 t = acc[ai][0][m][n] * nrs, p = (acc[ai][0][m][n] * acc[ai][1][m][n]) * rs2;
; #pragma unroll
;                     for (int j = 0; j < 4; ++j) o[4 * n + j] = p[j] * fast_rcp(1.0f + __builtin_amdgcn_exp2f(t[j]));
;                 }
;                 u32x4 w; w.x = cvt_pk_bf16(o[0], o[1]); w.y = cvt_pk_bf16(o[2], o[3]); w.z = cvt_pk_bf16(o[4], o[5]); w.w = cvt_pk_bf16(o[6], o[7]);
;                 *(u32x4*)(O + (size_t)r * ldo + col0) = w;
	v_mul_f32_e32 v205, v249, v249
	v_pk_mul_f32 v[120:121], v[120:121], v[230:231] op_sel_hi:[1,0]
	v_pk_mul_f32 v[122:123], v[122:123], v[230:231] op_sel_hi:[1,0]
	v_pk_mul_f32 v[116:117], v[116:117], v[230:231] op_sel_hi:[1,0]
	v_pk_mul_f32 v[118:119], v[118:119], v[230:231] op_sel_hi:[1,0]
	v_exp_f32_e32 v120, v120
	v_exp_f32_e32 v121, v121
	v_exp_f32_e32 v122, v122
	v_exp_f32_e32 v123, v123
	v_exp_f32_e32 v116, v116
	v_exp_f32_e32 v117, v117
	v_exp_f32_e32 v118, v118
	v_exp_f32_e32 v119, v119
	v_pk_mul_f32 v[124:125], v[124:125], v[230:231] op_sel:[0,1] op_sel_hi:[1,1]
	v_pk_mul_f32 v[126:127], v[126:127], v[230:231] op_sel:[0,1] op_sel_hi:[1,1]
	v_pk_mul_f32 v[112:113], v[112:113], v[230:231] op_sel:[0,1] op_sel_hi:[1,1]
	v_pk_mul_f32 v[114:115], v[114:115], v[230:231] op_sel:[0,1] op_sel_hi:[1,1]
	v_pk_add_f32 v[120:121], v[120:121], 1.0 op_sel_hi:[1,0]
	v_pk_add_f32 v[122:123], v[122:123], 1.0 op_sel_hi:[1,0]
	v_pk_add_f32 v[116:117], v[116:117], 1.0 op_sel_hi:[1,0]
	v_pk_add_f32 v[118:119], v[118:119], 1.0 op_sel_hi:[1,0]
	v_rcp_f32_e32 v120, v120
	v_rcp_f32_e32 v121, v121
	v_rcp_f32_e32 v122, v122
	v_rcp_f32_e32 v123, v123
	v_rcp_f32_e32 v116, v116
	v_rcp_f32_e32 v117, v117
	v_rcp_f32_e32 v118, v118
	v_rcp_f32_e32 v119, v119
	v_mad_i64_i32 v[208:209], s[4:5], v162, s67, v[220:221]
	v_lshl_add_u64 v[208:209], v[208:209], 0, v[250:251]
	v_pk_mul_f32 v[124:125], v[124:125], v[120:121]
	v_pk_mul_f32 v[126:127], v[126:127], v[122:123]
	v_pk_mul_f32 v[112:113], v[112:113], v[116:117]
	v_pk_mul_f32 v[114:115], v[114:115], v[118:119]
	v_cvt_pk_bf16_f32 v120, v124, v125
	v_cvt_pk_bf16_f32 v121, v126, v127
	v_cvt_pk_bf16_f32 v122, v112, v113
	v_cvt_pk_bf16_f32 v123, v114, v115
	global_store_dwordx4 v[208:209], v[120:123], off
	v_pk_mul_f32 v[108:109], v[108:109], v[232:233] op_sel_hi:[1,0]
	v_pk_mul_f32 v[110:111], v[110:111], v[232:233] op_sel_hi:[1,0]
	v_pk_mul_f32 v[100:101], v[100:101], v[232:233] op_sel_hi:[1,0]
	v_pk_mul_f32 v[102:103], v[102:103], v[232:233] op_sel_hi:[1,0]
	v_exp_f32_e32 v108, v108
	v_exp_f32_e32 v109, v109
	v_exp_f32_e32 v110, v110
	v_exp_f32_e32 v111, v111
	v_exp_f32_e32 v100, v100
	v_exp_f32_e32 v101, v101
	v_exp_f32_e32 v102, v102
	v_exp_f32_e32 v103, v103
	v_pk_mul_f32 v[104:105], v[104:105], v[232:233] op_sel:[0,1] op_sel_hi:[1,1]
	v_pk_mul_f32 v[106:107], v[106:107], v[232:233] op_sel:[0,1] op_sel_hi:[1,1]
	v_pk_mul_f32 v[96:97], v[96:97], v[232:233] op_sel:[0,1] op_sel_hi:[1,1]
	v_pk_mul_f32 v[98:99], v[98:99], v[232:233] op_sel:[0,1] op_sel_hi:[1,1]
	v_pk_add_f32 v[108:109], v[108:109], 1.0 op_sel_hi:[1,0]
	v_pk_add_f32 v[110:111], v[110:111], 1.0 op_sel_hi:[1,0]
	v_pk_add_f32 v[100:101], v[100:101], 1.0 op_sel_hi:[1,0]
	v_pk_add_f32 v[102:103], v[102:103], 1.0 op_sel_hi:[1,0]
	v_rcp_f32_e32 v108, v108
	v_rcp_f32_e32 v109, v109
	v_rcp_f32_e32 v110, v110
	v_rcp_f32_e32 v111, v111
	v_rcp_f32_e32 v100, v100
	v_rcp_f32_e32 v101, v101
	v_rcp_f32_e32 v102, v102
	v_rcp_f32_e32 v103, v103
	v_mad_i64_i32 v[208:209], s[4:5], v160, s67, v[220:221]
	v_lshl_add_u64 v[208:209], v[208:209], 0, v[250:251]
	v_pk_mul_f32 v[104:105], v[104:105], v[108:109]
	v_pk_mul_f32 v[106:107], v[106:107], v[110:111]
	v_pk_mul_f32 v[96:97], v[96:97], v[100:101]
	v_pk_mul_f32 v[98:99], v[98:99], v[102:103]
	v_cvt_pk_bf16_f32 v108, v104, v105
	v_cvt_pk_bf16_f32 v109, v106, v107
	v_cvt_pk_bf16_f32 v110, v96, v97
	v_cvt_pk_bf16_f32 v111, v98, v99
	global_store_dwordx4 v[208:209], v[108:111], off
	v_pk_mul_f32 v[92:93], v[92:93], v[234:235] op_sel_hi:[1,0]
	v_pk_mul_f32 v[94:95], v[94:95], v[234:235] op_sel_hi:[1,0]
	v_pk_mul_f32 v[84:85], v[84:85], v[234:235] op_sel_hi:[1,0]
	v_pk_mul_f32 v[86:87], v[86:87], v[234:235] op_sel_hi:[1,0]
	v_exp_f32_e32 v92, v92
	v_exp_f32_e32 v93, v93
	v_exp_f32_e32 v94, v94
	v_exp_f32_e32 v95, v95
	v_exp_f32_e32 v84, v84
	v_exp_f32_e32 v85, v85
	v_exp_f32_e32 v86, v86
	v_exp_f32_e32 v87, v87
	v_pk_mul_f32 v[88:89], v[88:89], v[234:235] op_sel:[0,1] op_sel_hi:[1,1]
	v_pk_mul_f32 v[90:91], v[90:91], v[234:235] op_sel:[0,1] op_sel_hi:[1,1]
	v_pk_mul_f32 v[80:81], v[80:81], v[234:235] op_sel:[0,1] op_sel_hi:[1,1]
	v_pk_mul_f32 v[82:83], v[82:83], v[234:235] op_sel:[0,1] op_sel_hi:[1,1]
	v_pk_add_f32 v[92:93], v[92:93], 1.0 op_sel_hi:[1,0]
	v_pk_add_f32 v[94:95], v[94:95], 1.0 op_sel_hi:[1,0]
	v_pk_add_f32 v[84:85], v[84:85], 1.0 op_sel_hi:[1,0]
	v_pk_add_f32 v[86:87], v[86:87], 1.0 op_sel_hi:[1,0]
	v_rcp_f32_e32 v92, v92
	v_rcp_f32_e32 v93, v93
	v_rcp_f32_e32 v94, v94
	v_rcp_f32_e32 v95, v95
	v_rcp_f32_e32 v84, v84
	v_rcp_f32_e32 v85, v85
	v_rcp_f32_e32 v86, v86
	v_rcp_f32_e32 v87, v87
	v_mad_i64_i32 v[208:209], s[4:5], v158, s67, v[220:221]
	v_lshl_add_u64 v[208:209], v[208:209], 0, v[250:251]
	v_pk_mul_f32 v[88:89], v[88:89], v[92:93]
	v_pk_mul_f32 v[90:91], v[90:91], v[94:95]
	v_pk_mul_f32 v[80:81], v[80:81], v[84:85]
	v_pk_mul_f32 v[82:83], v[82:83], v[86:87]
	v_cvt_pk_bf16_f32 v92, v88, v89
	v_cvt_pk_bf16_f32 v93, v90, v91
	v_cvt_pk_bf16_f32 v94, v80, v81
	v_cvt_pk_bf16_f32 v95, v82, v83
	global_store_dwordx4 v[208:209], v[92:95], off
	v_pk_mul_f32 v[76:77], v[76:77], v[184:185] op_sel_hi:[1,0]
	v_pk_mul_f32 v[78:79], v[78:79], v[184:185] op_sel_hi:[1,0]
	v_pk_mul_f32 v[68:69], v[68:69], v[184:185] op_sel_hi:[1,0]
	v_pk_mul_f32 v[70:71], v[70:71], v[184:185] op_sel_hi:[1,0]
	v_exp_f32_e32 v76, v76
	v_exp_f32_e32 v77, v77
	v_exp_f32_e32 v78, v78
	v_exp_f32_e32 v79, v79
	v_exp_f32_e32 v68, v68
	v_exp_f32_e32 v69, v69
	v_exp_f32_e32 v70, v70
	v_exp_f32_e32 v71, v71
	v_pk_mul_f32 v[72:73], v[72:73], v[184:185] op_sel:[0,1] op_sel_hi:[1,1]
	v_pk_mul_f32 v[74:75], v[74:75], v[184:185] op_sel:[0,1] op_sel_hi:[1,1]
; __device__ __forceinline__ unsigned cvt_pk_bf16(float lo, float hi) { unsigned r; asm volatile("v_cvt_pk_bf16_f32 %0, %1, %2" : "=v"(r) : "v"(lo), "v"(hi)); return r; }
; __device__ __forceinline__ float fast_rcp(float x) { return __builtin_amdgcn_rcpf(x); }
; __device__ __forceinline__ unsigned cvt_pk_bf16(float lo, float hi) { const f32x2 v = {lo, hi}; const bf16x2_t b = __builtin_convertvector(v, bf16x2_t); return __builtin_bit_cast(unsigned, b); }
;     __device__ __forceinline__ void operator()(const f32x4 (&acc)[2][2][4][2], const Unit& u, int wr, int wc, int fr, int fq) const {
;     ...
;             for (int m = 0; m < 4; ++m) {
;                 const int r = row0 + ai * HALF + m * 16; const float rs = rsv[ai][m], nrs = rs * -1.4426950408889634f, rs2 = rs * rs;
;                 float o[8];
; #pragma unroll
;                 for (int n = 0; n < 2; ++n) {
;                     const f32x4 t = acc[ai][0][m][n] * nrs, p = (acc[ai][0][m][n] * acc[ai][1][m][n]) * rs2;
; #pragma unroll
;                     for (int j = 0; j < 4; ++j) o[4 * n + j] = p[j] * fast_rcp(1.0f + __builtin_amdgcn_exp2f(t[j]));
;                 }
;                 u32x4 w; w.x = cvt_pk_bf16(o[0], o[1]); w.y = cvt_pk_bf16(o[2], o[3]); w.z = cvt_pk_bf16(o[4], o[5]); w.w = cvt_pk_bf16(o[6], o[7]);
;                 *(u32x4*)(O + (size_t)r * ldo + col0) = w;
	v_pk_mul_f32 v[64:65], v[64:65], v[184:185] op_sel:[0,1] op_sel_hi:[1,1]
	v_pk_mul_f32 v[66:67], v[66:67], v[184:185] op_sel:[0,1] op_sel_hi:[1,1]
	v_pk_add_f32 v[76:77], v[76:77], 1.0 op_sel_hi:[1,0]
	v_pk_add_f32 v[78:79], v[78:79], 1.0 op_sel_hi:[1,0]
	v_pk_add_f32 v[68:69], v[68:69], 1.0 op_sel_hi:[1,0]
	v_pk_add_f32 v[70:71], v[70:71], 1.0 op_sel_hi:[1,0]
	v_rcp_f32_e32 v76, v76
	v_rcp_f32_e32 v77, v77
	v_rcp_f32_e32 v78, v78
	v_rcp_f32_e32 v79, v79
	v_rcp_f32_e32 v68, v68
	v_rcp_f32_e32 v69, v69
	v_rcp_f32_e32 v70, v70
	v_rcp_f32_e32 v71, v71
	v_mad_i64_i32 v[208:209], s[4:5], v156, s67, v[220:221]
	v_lshl_add_u64 v[208:209], v[208:209], 0, v[250:251]
	v_pk_mul_f32 v[72:73], v[72:73], v[76:77]
	v_pk_mul_f32 v[74:75], v[74:75], v[78:79]
	v_pk_mul_f32 v[64:65], v[64:65], v[68:69]
	v_pk_mul_f32 v[66:67], v[66:67], v[70:71]
	v_cvt_pk_bf16_f32 v76, v72, v73
	v_cvt_pk_bf16_f32 v77, v74, v75
	v_cvt_pk_bf16_f32 v78, v64, v65
	v_cvt_pk_bf16_f32 v79, v66, v67
	global_store_dwordx4 v[208:209], v[76:79], off
	v_pk_mul_f32 v[60:61], v[60:61], v[186:187] op_sel_hi:[1,0]
	v_pk_mul_f32 v[62:63], v[62:63], v[186:187] op_sel_hi:[1,0]
	v_pk_mul_f32 v[52:53], v[52:53], v[186:187] op_sel_hi:[1,0]
	v_pk_mul_f32 v[54:55], v[54:55], v[186:187] op_sel_hi:[1,0]
	v_exp_f32_e32 v60, v60
	v_exp_f32_e32 v61, v61
	v_exp_f32_e32 v62, v62
	v_exp_f32_e32 v63, v63
	v_exp_f32_e32 v52, v52
	v_exp_f32_e32 v53, v53
	v_exp_f32_e32 v54, v54
	v_exp_f32_e32 v55, v55
	v_pk_mul_f32 v[56:57], v[56:57], v[186:187] op_sel:[0,1] op_sel_hi:[1,1]
	v_pk_mul_f32 v[58:59], v[58:59], v[186:187] op_sel:[0,1] op_sel_hi:[1,1]
	v_pk_mul_f32 v[48:49], v[48:49], v[186:187] op_sel:[0,1] op_sel_hi:[1,1]
	v_pk_mul_f32 v[50:51], v[50:51], v[186:187] op_sel:[0,1] op_sel_hi:[1,1]
	v_pk_add_f32 v[60:61], v[60:61], 1.0 op_sel_hi:[1,0]
	v_pk_add_f32 v[62:63], v[62:63], 1.0 op_sel_hi:[1,0]
	v_pk_add_f32 v[52:53], v[52:53], 1.0 op_sel_hi:[1,0]
	v_pk_add_f32 v[54:55], v[54:55], 1.0 op_sel_hi:[1,0]
	v_rcp_f32_e32 v60, v60
	v_rcp_f32_e32 v61, v61
	v_rcp_f32_e32 v62, v62
	v_rcp_f32_e32 v63, v63
	v_rcp_f32_e32 v52, v52
	v_rcp_f32_e32 v53, v53
	v_rcp_f32_e32 v54, v54
	v_rcp_f32_e32 v55, v55
	v_mad_i64_i32 v[208:209], s[4:5], v154, s67, v[220:221]
	v_lshl_add_u64 v[208:209], v[208:209], 0, v[250:251]
	v_pk_mul_f32 v[56:57], v[56:57], v[60:61]
	v_pk_mul_f32 v[58:59], v[58:59], v[62:63]
	v_pk_mul_f32 v[48:49], v[48:49], v[52:53]
	v_pk_mul_f32 v[50:51], v[50:51], v[54:55]
	v_cvt_pk_bf16_f32 v60, v56, v57
	v_cvt_pk_bf16_f32 v61, v58, v59
	v_cvt_pk_bf16_f32 v62, v48, v49
	v_cvt_pk_bf16_f32 v63, v50, v51
	global_store_dwordx4 v[208:209], v[60:63], off
	v_pk_mul_f32 v[44:45], v[44:45], v[188:189] op_sel_hi:[1,0]
	v_pk_mul_f32 v[46:47], v[46:47], v[188:189] op_sel_hi:[1,0]
	v_pk_mul_f32 v[36:37], v[36:37], v[188:189] op_sel_hi:[1,0]
	v_pk_mul_f32 v[38:39], v[38:39], v[188:189] op_sel_hi:[1,0]
	v_exp_f32_e32 v44, v44
	v_exp_f32_e32 v45, v45
	v_exp_f32_e32 v46, v46
	v_exp_f32_e32 v47, v47
	v_exp_f32_e32 v36, v36
	v_exp_f32_e32 v37, v37
	v_exp_f32_e32 v38, v38
	v_exp_f32_e32 v39, v39
	v_pk_mul_f32 v[40:41], v[40:41], v[188:189] op_sel:[0,1] op_sel_hi:[1,1]
	v_pk_mul_f32 v[42:43], v[42:43], v[188:189] op_sel:[0,1] op_sel_hi:[1,1]
	v_pk_mul_f32 v[32:33], v[32:33], v[188:189] op_sel:[0,1] op_sel_hi:[1,1]
	v_pk_mul_f32 v[34:35], v[34:35], v[188:189] op_sel:[0,1] op_sel_hi:[1,1]
	v_pk_add_f32 v[44:45], v[44:45], 1.0 op_sel_hi:[1,0]
	v_pk_add_f32 v[46:47], v[46:47], 1.0 op_sel_hi:[1,0]
	v_pk_add_f32 v[36:37], v[36:37], 1.0 op_sel_hi:[1,0]
	v_pk_add_f32 v[38:39], v[38:39], 1.0 op_sel_hi:[1,0]
	v_rcp_f32_e32 v44, v44
	v_rcp_f32_e32 v45, v45
	v_rcp_f32_e32 v46, v46
	v_rcp_f32_e32 v47, v47
	v_rcp_f32_e32 v36, v36
	v_rcp_f32_e32 v37, v37
	v_rcp_f32_e32 v38, v38
; __device__ __forceinline__ unsigned cvt_pk_bf16(float lo, float hi) { unsigned r; asm volatile("v_cvt_pk_bf16_f32 %0, %1, %2" : "=v"(r) : "v"(lo), "v"(hi)); return r; }
; __device__ __forceinline__ float fast_rcp(float x) { return __builtin_amdgcn_rcpf(x); }
; #define PG8_BAR __builtin_amdgcn_s_barrier()
; __device__ __forceinline__ unsigned cvt_pk_bf16(float lo, float hi) { const f32x2 v = {lo, hi}; const bf16x2_t b = __builtin_convertvector(v, bf16x2_t); return __builtin_bit_cast(unsigned, b); }
;     __device__ __forceinline__ void operator()(const f32x4 (&acc)[2][2][4][2], const Unit& u, int wr, int wc, int fr, int fq) const {
;     ...
;             for (int m = 0; m < 4; ++m) {
;                 const int r = row0 + ai * HALF + m * 16; const float rs = rsv[ai][m], nrs = rs * -1.4426950408889634f, rs2 = rs * rs;
;                 float o[8];
; #pragma unroll
;                 for (int n = 0; n < 2; ++n) {
;                     const f32x4 t = acc[ai][0][m][n] * nrs, p = (acc[ai][0][m][n] * acc[ai][1][m][n]) * rs2;
; #pragma unroll
;                     for (int j = 0; j < 4; ++j) o[4 * n + j] = p[j] * fast_rcp(1.0f + __builtin_amdgcn_exp2f(t[j]));
;                 }
;                 u32x4 w; w.x = cvt_pk_bf16(o[0], o[1]); w.y = cvt_pk_bf16(o[2], o[3]); w.z = cvt_pk_bf16(o[4], o[5]); w.w = cvt_pk_bf16(o[6], o[7]);
;                 *(u32x4*)(O + (size_t)r * ldo + col0) = w;
; template <class Epi, class Sched, bool ALIGN_EPI = false, bool SP2 = false>
; __device__ __forceinline__ void gemm_phase(PG8_LAS unsigned char* lds, const Gemm g, const Sched& S, const Epi& E) {
;     ...
;         if constexpr (!Epi::AFTER_DRAIN) { E(acc, cur, wr, wc, fr, fq); S.done(cur); }
;         if (!has_next) break;
; #pragma unroll
;         for (int a = 0; a < 2; ++a)
; #pragma unroll
;             for (int b = 0; b < 2; ++b)
; #pragma unroll
;                 for (int m = 0; m < 4; ++m)
; #pragma unroll
;                     for (int n = 0; n < 2; ++n) acc[a][b][m][n] = (f32x4){0.f, 0.f, 0.f, 0.f};
;         cur = nxt; cA = nA; cB = nB; ++ui;
;         if constexpr (ALIGN_EPI) { if (wr == 1) PG8_BAR; }
	v_rcp_f32_e32 v39, v39
	v_mad_i64_i32 v[208:209], s[4:5], v152, s67, v[220:221]
	v_lshl_add_u64 v[208:209], v[208:209], 0, v[250:251]
	v_pk_mul_f32 v[40:41], v[40:41], v[44:45]
	v_pk_mul_f32 v[42:43], v[42:43], v[46:47]
	v_pk_mul_f32 v[32:33], v[32:33], v[36:37]
	v_pk_mul_f32 v[34:35], v[34:35], v[38:39]
	v_cvt_pk_bf16_f32 v44, v40, v41
	v_cvt_pk_bf16_f32 v45, v42, v43
	v_cvt_pk_bf16_f32 v46, v32, v33
	v_cvt_pk_bf16_f32 v47, v34, v35
	global_store_dwordx4 v[208:209], v[44:47], off
	v_pk_mul_f32 v[28:29], v[28:29], v[190:191] op_sel_hi:[1,0]
	v_pk_mul_f32 v[30:31], v[30:31], v[190:191] op_sel_hi:[1,0]
	v_pk_mul_f32 v[20:21], v[20:21], v[190:191] op_sel_hi:[1,0]
	v_pk_mul_f32 v[22:23], v[22:23], v[190:191] op_sel_hi:[1,0]
	v_exp_f32_e32 v28, v28
	v_exp_f32_e32 v29, v29
	v_exp_f32_e32 v30, v30
	v_exp_f32_e32 v31, v31
	v_exp_f32_e32 v20, v20
	v_exp_f32_e32 v21, v21
	v_exp_f32_e32 v22, v22
	v_exp_f32_e32 v23, v23
	v_pk_mul_f32 v[24:25], v[24:25], v[190:191] op_sel:[0,1] op_sel_hi:[1,1]
	v_pk_mul_f32 v[26:27], v[26:27], v[190:191] op_sel:[0,1] op_sel_hi:[1,1]
	v_pk_mul_f32 v[16:17], v[16:17], v[190:191] op_sel:[0,1] op_sel_hi:[1,1]
	v_pk_mul_f32 v[18:19], v[18:19], v[190:191] op_sel:[0,1] op_sel_hi:[1,1]
	v_pk_add_f32 v[28:29], v[28:29], 1.0 op_sel_hi:[1,0]
	v_pk_add_f32 v[30:31], v[30:31], 1.0 op_sel_hi:[1,0]
	v_pk_add_f32 v[20:21], v[20:21], 1.0 op_sel_hi:[1,0]
	v_pk_add_f32 v[22:23], v[22:23], 1.0 op_sel_hi:[1,0]
	v_rcp_f32_e32 v28, v28
	v_rcp_f32_e32 v29, v29
	v_rcp_f32_e32 v30, v30
	v_rcp_f32_e32 v31, v31
	v_rcp_f32_e32 v20, v20
	v_rcp_f32_e32 v21, v21
	v_rcp_f32_e32 v22, v22
	v_rcp_f32_e32 v23, v23
	v_mad_i64_i32 v[208:209], s[4:5], v150, s67, v[220:221]
	v_lshl_add_u64 v[208:209], v[208:209], 0, v[250:251]
	v_pk_mul_f32 v[24:25], v[24:25], v[28:29]
	v_pk_mul_f32 v[26:27], v[26:27], v[30:31]
	v_pk_mul_f32 v[16:17], v[16:17], v[20:21]
	v_pk_mul_f32 v[18:19], v[18:19], v[22:23]
	v_cvt_pk_bf16_f32 v28, v24, v25
	v_cvt_pk_bf16_f32 v29, v26, v27
	v_cvt_pk_bf16_f32 v30, v16, v17
	v_cvt_pk_bf16_f32 v31, v18, v19
	global_store_dwordx4 v[208:209], v[28:31], off
	v_pk_mul_f32 v[12:13], v[12:13], v[204:205] op_sel_hi:[1,0]
	v_pk_mul_f32 v[14:15], v[14:15], v[204:205] op_sel_hi:[1,0]
	v_pk_mul_f32 v[4:5], v[4:5], v[204:205] op_sel_hi:[1,0]
	v_pk_mul_f32 v[6:7], v[6:7], v[204:205] op_sel_hi:[1,0]
	v_exp_f32_e32 v12, v12
	v_exp_f32_e32 v13, v13
	v_exp_f32_e32 v14, v14
	v_exp_f32_e32 v15, v15
	v_exp_f32_e32 v4, v4
	v_exp_f32_e32 v5, v5
	v_exp_f32_e32 v6, v6
	v_exp_f32_e32 v7, v7
	v_pk_mul_f32 v[8:9], v[8:9], v[204:205] op_sel:[0,1] op_sel_hi:[1,1]
	v_pk_mul_f32 v[10:11], v[10:11], v[204:205] op_sel:[0,1] op_sel_hi:[1,1]
	v_pk_mul_f32 v[0:1], v[0:1], v[204:205] op_sel:[0,1] op_sel_hi:[1,1]
	v_pk_mul_f32 v[2:3], v[2:3], v[204:205] op_sel:[0,1] op_sel_hi:[1,1]
	v_pk_add_f32 v[12:13], v[12:13], 1.0 op_sel_hi:[1,0]
	v_pk_add_f32 v[14:15], v[14:15], 1.0 op_sel_hi:[1,0]
	v_pk_add_f32 v[4:5], v[4:5], 1.0 op_sel_hi:[1,0]
	v_pk_add_f32 v[6:7], v[6:7], 1.0 op_sel_hi:[1,0]
	v_rcp_f32_e32 v12, v12
	v_rcp_f32_e32 v13, v13
	v_rcp_f32_e32 v14, v14
	v_rcp_f32_e32 v15, v15
	v_rcp_f32_e32 v4, v4
	v_rcp_f32_e32 v5, v5
	v_rcp_f32_e32 v6, v6
	v_rcp_f32_e32 v7, v7
	v_mad_i64_i32 v[208:209], s[4:5], v148, s67, v[220:221]
	v_lshl_add_u64 v[208:209], v[208:209], 0, v[250:251]
	v_pk_mul_f32 v[8:9], v[8:9], v[12:13]
	v_pk_mul_f32 v[10:11], v[10:11], v[14:15]
	v_pk_mul_f32 v[0:1], v[0:1], v[4:5]
	v_pk_mul_f32 v[2:3], v[2:3], v[6:7]
	v_cvt_pk_bf16_f32 v12, v8, v9
	v_cvt_pk_bf16_f32 v13, v10, v11
	v_cvt_pk_bf16_f32 v14, v0, v1
	v_cvt_pk_bf16_f32 v15, v2, v3
	global_store_dwordx4 v[208:209], v[12:15], off
	s_cbranch_vccnz .LBB0_1005
	s_andn2_b64 vcc, exec, s[14:15]
	s_cbranch_vccnz .LBB0_1004
	s_barrier
	s_branch .LBB0_1004
